# attention loops: K-fragment LDS reads batched ahead of the S-product MFMAs (NA, MLA) with counted lgkmcnt waits; redundant canonicalizing v_max x,x removed from row-max trees
# baseline (speedup 1.0000x reference)
.LBB0_697:
	s_xor_b64 s[36:37], s[10:11], -1
	s_cmp_lt_u32 s26, 32
	s_cselect_b32 s35, s6, s22
	s_cselect_b32 s33, s7, s23
	s_add_u32 s12, s35, s12
	s_addc_u32 s13, s33, s13
	v_lshl_add_u64 v[8:9], s[12:13], 0, v[2:3]
	s_add_i32 m0, s20, 0x6000
	ds_read_b128 v[130:133], v214
	ds_read_b128 v[134:137], v214 offset:1024
	ds_read_b128 v[142:145], v214 offset:2048
	ds_read_b128 v[150:153], v214 offset:3072
	global_load_lds_dwordx4 v[8:9], off
	v_xor_b32_e32 v126, 0x80000000, v42
	v_mov_b32_e32 v127, v126
	v_mov_b32_e32 v128, v126
	v_mov_b32_e32 v129, v126
	s_waitcnt lgkmcnt(0)
	s_nop 0
	v_mfma_f32_16x16x32_bf16 v[138:141], v[130:133], v[10:13], v[126:129]
	v_mfma_f32_16x16x32_bf16 v[126:129], v[142:145], v[10:13], v[126:129]
	v_mfma_f32_16x16x32_bf16 v[166:169], v[150:153], v[14:17], v[126:129]
	v_mfma_f32_16x16x32_bf16 v[170:173], v[134:137], v[14:17], v[138:141]
	s_nop 5
	v_xor_b32_e32 v126, 0x80000000, v43
	v_mov_b32_e32 v127, v126
	v_mov_b32_e32 v128, v126
	v_mov_b32_e32 v129, v126
	s_nop 1
	v_mfma_f32_16x16x32_bf16 v[138:141], v[130:133], v[18:21], v[126:129]
	v_mfma_f32_16x16x32_bf16 v[162:165], v[134:137], v[22:25], v[138:141]
	v_mfma_f32_16x16x32_bf16 v[126:129], v[142:145], v[18:21], v[126:129]
	s_nop 5
	v_xor_b32_e32 v138, 0x80000000, v44
	v_mov_b32_e32 v139, v138
	v_mov_b32_e32 v140, v138
	v_mov_b32_e32 v141, v138
	v_mfma_f32_16x16x32_bf16 v[126:129], v[150:153], v[22:25], v[126:129]
	s_nop 0
	v_mfma_f32_16x16x32_bf16 v[146:149], v[130:133], v[26:29], v[138:141]
	v_mfma_f32_16x16x32_bf16 v[138:141], v[142:145], v[26:29], v[138:141]
	v_mfma_f32_16x16x32_bf16 v[154:157], v[150:153], v[30:33], v[138:141]
	v_mfma_f32_16x16x32_bf16 v[158:161], v[134:137], v[30:33], v[146:149]
	s_nop 5
	v_xor_b32_e32 v138, 0x80000000, v45
	v_mov_b32_e32 v139, v138
	v_mov_b32_e32 v140, v138
	v_mov_b32_e32 v141, v138
	s_nop 1
	v_mfma_f32_16x16x32_bf16 v[130:133], v[130:133], v[34:37], v[138:141]
	v_mfma_f32_16x16x32_bf16 v[146:149], v[134:137], v[38:41], v[130:133]
	v_mfma_f32_16x16x32_bf16 v[130:133], v[142:145], v[34:37], v[138:141]
	v_mfma_f32_16x16x32_bf16 v[150:153], v[150:153], v[38:41], v[130:133]
	v_max_f32_e32 v7, v170, v171
	v_max_f32_e32 v8, v172, v173
	v_max_f32_e32 v174, v168, v168
	v_max_f32_e32 v9, v174, v169
	v_max3_f32 v9, v166, v167, v9
	v_max3_f32 v7, v7, v8, v9
	v_mov_b32_e32 v8, v7
	s_nop 1
	v_permlane16_swap_b32_e32 v7, v8
	ds_read_b128 v[130:133], v214 offset:4096
	ds_read_b128 v[134:137], v214 offset:5120
	ds_read_b128 v[138:141], v214 offset:6144
	ds_read_b128 v[142:145], v214 offset:7168
	v_max_f32_e32 v7, v7, v8
	v_mov_b32_e32 v8, v7
	s_nop 1
	v_permlane32_swap_b32_e32 v7, v8
	v_max_f32_e32 v7, v7, v8
	v_cndmask_b32_e64 v8, 0, 1, s[36:37]
	v_cmp_ne_u32_e64 s[54:55], 1, v8
	s_andn2_b64 vcc, exec, s[36:37]
	s_mov_b64 s[12:13], -1
	s_cbranch_vccnz .LBB0_700
	v_cmp_lt_f32_e32 vcc, s29, v7
	s_cbranch_vccz .LBB0_764
	v_max_f32_e32 v7, 0, v7

.LBB0_702:
	v_exp_f32_e32 v7, v170
	v_exp_f32_e32 v8, v171
	v_exp_f32_e32 v9, v172
	v_exp_f32_e32 v170, v173
	v_exp_f32_e32 v171, v166
	v_exp_f32_e32 v172, v167
	v_exp_f32_e32 v173, v168
	v_exp_f32_e32 v169, v169
	v_cvt_pk_bf16_f32 v166, v7, v8
	v_cvt_pk_bf16_f32 v167, v9, v170
	v_mov_b32_e32 v7, v6
	v_mov_b32_e32 v8, v6
	v_mov_b32_e32 v9, v6
	v_cvt_pk_bf16_f32 v168, v171, v172
	v_cvt_pk_bf16_f32 v169, v173, v169
	s_and_b64 vcc, exec, s[54:55]
	s_mov_b64 s[12:13], -1
	v_mfma_f32_16x16x32_bf16 v[122:125], v[6:9], v[166:169], v[122:125]
	v_max_f32_e32 v7, v162, v163
	s_waitcnt lgkmcnt(0)
	v_mfma_f32_16x16x32_bf16 v[114:117], v[130:133], v[166:169], v[114:117]
	v_max_f32_e32 v8, v164, v165
	v_mfma_f32_16x16x32_bf16 v[110:113], v[134:137], v[166:169], v[110:113]
	v_mfma_f32_16x16x32_bf16 v[106:109], v[138:141], v[166:169], v[106:109]
	v_mfma_f32_16x16x32_bf16 v[98:101], v[142:145], v[166:169], v[98:101]
	v_max_f32_e32 v166, v128, v128
	v_max_f32_e32 v9, v166, v129
	v_max3_f32 v9, v126, v127, v9
	v_max3_f32 v7, v7, v8, v9
	v_mov_b32_e32 v8, v7
	s_nop 1
	v_permlane16_swap_b32_e32 v7, v8
	v_max_f32_e32 v7, v7, v8
	v_mov_b32_e32 v8, v7
	s_nop 1
	v_permlane32_swap_b32_e32 v7, v8
	v_max_f32_e32 v7, v7, v8
	s_cbranch_vccnz .LBB0_705
	v_cmp_lt_f32_e32 vcc, s29, v7
	s_cbranch_vccz .LBB0_765
	v_max_f32_e32 v7, 0, v7

.LBB0_707:
	v_exp_f32_e32 v7, v162
	v_exp_f32_e32 v8, v163
	v_exp_f32_e32 v9, v164
	v_exp_f32_e32 v163, v165
	v_exp_f32_e32 v126, v126
	v_exp_f32_e32 v127, v127
	v_exp_f32_e32 v128, v128
	v_exp_f32_e32 v129, v129
	v_cvt_pk_bf16_f32 v162, v7, v8
	v_cvt_pk_bf16_f32 v163, v9, v163
	v_mov_b32_e32 v7, v6
	v_mov_b32_e32 v8, v6
	v_mov_b32_e32 v9, v6
	v_cvt_pk_bf16_f32 v164, v126, v127
	v_cvt_pk_bf16_f32 v165, v128, v129
	s_and_b64 vcc, exec, s[54:55]
	s_mov_b64 s[12:13], -1
	v_mfma_f32_16x16x32_bf16 v[126:129], v[130:133], v[162:165], v[90:93]
	v_mfma_f32_16x16x32_bf16 v[90:93], v[134:137], v[162:165], v[86:89]
	v_mfma_f32_16x16x32_bf16 v[86:89], v[138:141], v[162:165], v[82:85]
	v_mfma_f32_16x16x32_bf16 v[82:85], v[142:145], v[162:165], v[78:81]
	v_mfma_f32_16x16x32_bf16 v[78:81], v[6:9], v[162:165], v[118:121]
	v_max_f32_e32 v7, v158, v159
	v_max_f32_e32 v8, v160, v161
	v_max_f32_e32 v118, v156, v156
	v_max_f32_e32 v9, v118, v157
	v_max3_f32 v9, v154, v155, v9
	v_max3_f32 v7, v7, v8, v9
	v_mov_b32_e32 v8, v7
	s_nop 1
	v_permlane16_swap_b32_e32 v7, v8
	v_max_f32_e32 v7, v7, v8
	v_mov_b32_e32 v8, v7
	s_nop 1
	v_permlane32_swap_b32_e32 v7, v8
	v_max_f32_e32 v7, v7, v8
	s_cbranch_vccnz .LBB0_710
	v_cmp_lt_f32_e32 vcc, s29, v7
	s_cbranch_vccz .LBB0_766
	v_max_f32_e32 v7, 0, v7

.LBB0_712:
	v_exp_f32_e32 v7, v158
	v_exp_f32_e32 v8, v159
	v_exp_f32_e32 v9, v160
	v_exp_f32_e32 v119, v161
	v_exp_f32_e32 v120, v154
	v_exp_f32_e32 v121, v155
	v_exp_f32_e32 v154, v156
	v_exp_f32_e32 v155, v157
	v_cvt_pk_bf16_f32 v118, v7, v8
	v_cvt_pk_bf16_f32 v119, v9, v119
	v_mov_b32_e32 v7, v6
	v_mov_b32_e32 v8, v6
	v_mov_b32_e32 v9, v6
	v_cvt_pk_bf16_f32 v120, v120, v121
	v_cvt_pk_bf16_f32 v121, v154, v155
	s_and_b64 vcc, exec, s[54:55]
	s_mov_b64 s[12:13], -1
	v_mfma_f32_16x16x32_bf16 v[102:105], v[6:9], v[118:121], v[102:105]
	v_max_f32_e32 v7, v146, v147
	v_mfma_f32_16x16x32_bf16 v[74:77], v[130:133], v[118:121], v[74:77]
	v_max_f32_e32 v8, v148, v149
	v_mfma_f32_16x16x32_bf16 v[70:73], v[134:137], v[118:121], v[70:73]
	v_mfma_f32_16x16x32_bf16 v[66:69], v[138:141], v[118:121], v[66:69]
	v_mfma_f32_16x16x32_bf16 v[62:65], v[142:145], v[118:121], v[62:65]
	v_max_f32_e32 v118, v152, v152
	v_max_f32_e32 v9, v118, v153
	v_max3_f32 v9, v150, v151, v9
	v_max3_f32 v7, v7, v8, v9
	v_mov_b32_e32 v8, v7
	s_nop 1
	v_permlane16_swap_b32_e32 v7, v8
	v_max_f32_e32 v7, v7, v8
	v_mov_b32_e32 v8, v7
	s_nop 1
	v_permlane32_swap_b32_e32 v7, v8
	v_max_f32_e32 v7, v7, v8
	s_cbranch_vccnz .LBB0_715
	v_cmp_lt_f32_e32 vcc, s29, v7
	s_cbranch_vccz .LBB0_767
	v_max_f32_e32 v7, 0, v7

.LBB0_722:
	ds_read_b128 v[54:57], v214 offset:8192
	ds_read_b128 v[58:61], v214 offset:9216
	v_xor_b32_e32 v94, 0x80000000, v43
	v_mov_b32_e32 v95, v94
	v_mov_b32_e32 v96, v94
	v_mov_b32_e32 v97, v94
	ds_read_b128 v[118:121], v214 offset:10240
	ds_read_b128 v[142:145], v214 offset:11264
	s_waitcnt lgkmcnt(0)
	v_mfma_f32_16x16x32_bf16 v[154:157], v[54:57], v[18:21], v[94:97]
	v_xor_b32_e32 v46, 0x80000000, v42
	v_mov_b32_e32 v47, v46
	v_mov_b32_e32 v48, v46
	v_mfma_f32_16x16x32_bf16 v[182:185], v[58:61], v[22:25], v[154:157]
	v_mov_b32_e32 v49, v46
	s_nop 2
	v_xor_b32_e32 v154, 0x80000000, v44
	v_mov_b32_e32 v155, v154
	v_mov_b32_e32 v156, v154
	v_mov_b32_e32 v157, v154
	v_mfma_f32_16x16x32_bf16 v[50:53], v[54:57], v[10:13], v[46:49]
	s_nop 0
	v_mfma_f32_16x16x32_bf16 v[158:161], v[54:57], v[26:29], v[154:157]
	v_mfma_f32_16x16x32_bf16 v[154:157], v[118:121], v[26:29], v[154:157]
	v_mfma_f32_16x16x32_bf16 v[174:177], v[142:145], v[30:33], v[154:157]
	v_mfma_f32_16x16x32_bf16 v[46:49], v[118:121], v[10:13], v[46:49]
	s_nop 5
	v_xor_b32_e32 v154, 0x80000000, v45
	v_mov_b32_e32 v155, v154
	v_mov_b32_e32 v156, v154
	v_mov_b32_e32 v157, v154
	v_mfma_f32_16x16x32_bf16 v[94:97], v[118:121], v[18:21], v[94:97]
	s_nop 0
	v_mfma_f32_16x16x32_bf16 v[54:57], v[54:57], v[34:37], v[154:157]
	v_mfma_f32_16x16x32_bf16 v[170:173], v[58:61], v[38:41], v[54:57]
	v_mfma_f32_16x16x32_bf16 v[54:57], v[118:121], v[34:37], v[154:157]
	v_mfma_f32_16x16x32_bf16 v[50:53], v[58:61], v[14:17], v[50:53]
	v_mfma_f32_16x16x32_bf16 v[46:49], v[142:145], v[14:17], v[46:49]
	v_mfma_f32_16x16x32_bf16 v[94:97], v[142:145], v[22:25], v[94:97]
	v_mfma_f32_16x16x32_bf16 v[178:181], v[58:61], v[30:33], v[158:161]
	v_mfma_f32_16x16x32_bf16 v[166:169], v[142:145], v[38:41], v[54:57]
	s_nop 3
	v_max_f32_e32 v7, v50, v51
	v_max_f32_e32 v8, v52, v53
	v_max_f32_e32 v54, v48, v48
	v_max_f32_e32 v9, v54, v49
	v_max3_f32 v9, v46, v47, v9
	v_max3_f32 v7, v7, v8, v9
	v_mov_b32_e32 v8, v7
	s_nop 1
	v_permlane16_swap_b32_e32 v7, v8
	ds_read_b128 v[142:145], v214 offset:12288
	ds_read_b128 v[154:157], v214 offset:13312
	ds_read_b128 v[158:161], v214 offset:14336
	ds_read_b128 v[162:165], v214 offset:15360
	v_max_f32_e32 v7, v7, v8
	v_mov_b32_e32 v8, v7
	s_nop 1
	v_permlane32_swap_b32_e32 v7, v8
	v_max_f32_e32 v7, v7, v8
	v_cmp_lt_f32_e32 vcc, s29, v7
	s_cbranch_vccz .LBB0_724
	v_max_f32_e32 v7, 0, v7
	v_exp_f32_e64 v8, -v7
	v_add_f32_e32 v42, v42, v7
	v_sub_f32_e32 v50, v50, v7
	v_sub_f32_e32 v51, v51, v7
	v_pk_mul_f32 v[124:125], v[124:125], v[8:9] op_sel_hi:[1,0]
	v_pk_mul_f32 v[122:123], v[122:123], v[8:9] op_sel_hi:[1,0]
	v_pk_mul_f32 v[116:117], v[116:117], v[8:9] op_sel_hi:[1,0]
	v_pk_mul_f32 v[114:115], v[114:115], v[8:9] op_sel_hi:[1,0]
	v_pk_mul_f32 v[112:113], v[112:113], v[8:9] op_sel_hi:[1,0]
	v_pk_mul_f32 v[110:111], v[110:111], v[8:9] op_sel_hi:[1,0]
	v_pk_mul_f32 v[108:109], v[108:109], v[8:9] op_sel_hi:[1,0]
	v_pk_mul_f32 v[106:107], v[106:107], v[8:9] op_sel_hi:[1,0]
	v_pk_mul_f32 v[100:101], v[100:101], v[8:9] op_sel_hi:[1,0]
	v_pk_mul_f32 v[98:99], v[98:99], v[8:9] op_sel_hi:[1,0]
	v_sub_f32_e32 v52, v52, v7
	v_sub_f32_e32 v53, v53, v7
	v_sub_f32_e32 v46, v46, v7
	v_sub_f32_e32 v47, v47, v7
	v_sub_f32_e32 v48, v48, v7
	v_sub_f32_e32 v49, v49, v7
.LBB0_724:
	v_exp_f32_e32 v7, v50
	v_exp_f32_e32 v8, v51
	v_exp_f32_e32 v9, v52
	v_exp_f32_e32 v50, v53
	v_exp_f32_e32 v46, v46
	v_exp_f32_e32 v47, v47
	v_exp_f32_e32 v48, v48
	v_exp_f32_e32 v49, v49
	v_cvt_pk_bf16_f32 v118, v7, v8
	v_cvt_pk_bf16_f32 v119, v9, v50
	v_cvt_pk_bf16_f32 v120, v46, v47
	v_cvt_pk_bf16_f32 v121, v48, v49
	v_mov_b32_e32 v7, v6
	v_mov_b32_e32 v8, v6
	s_waitcnt lgkmcnt(0)
	v_mfma_f32_16x16x32_bf16 v[46:49], v[162:165], v[118:121], v[98:101]
	v_mov_b32_e32 v9, v6
	s_nop 1
	v_max_f32_e32 v98, v182, v183
	v_max_f32_e32 v99, v184, v185
	v_max_f32_e32 v101, v96, v96
	v_max_f32_e32 v100, v101, v97
	v_max3_f32 v100, v94, v95, v100
	v_max3_f32 v98, v98, v99, v100
	v_mov_b32_e32 v99, v98
	s_nop 1
	v_permlane16_swap_b32_e32 v98, v99
	v_max_f32_e32 v98, v98, v99
	v_mov_b32_e32 v99, v98
	v_mfma_f32_16x16x32_bf16 v[58:61], v[142:145], v[118:121], v[114:117]
	s_nop 0
	v_permlane32_swap_b32_e32 v98, v99
	v_mfma_f32_16x16x32_bf16 v[54:57], v[154:157], v[118:121], v[110:113]
	v_max_f32_e32 v98, v98, v99
	v_cmp_lt_f32_e32 vcc, s29, v98
	v_mfma_f32_16x16x32_bf16 v[50:53], v[158:161], v[118:121], v[106:109]
	v_mfma_f32_16x16x32_bf16 v[118:121], v[6:9], v[118:121], v[122:125]
	s_cbranch_vccz .LBB0_726
	v_max_f32_e32 v99, 0, v98
	v_exp_f32_e64 v98, -v99
	v_add_f32_e32 v43, v43, v99
	v_sub_f32_e32 v182, v182, v99
	v_sub_f32_e32 v183, v183, v99
	v_pk_mul_f32 v[80:81], v[80:81], v[98:99] op_sel_hi:[1,0]
	v_pk_mul_f32 v[78:79], v[78:79], v[98:99] op_sel_hi:[1,0]
	v_pk_mul_f32 v[128:129], v[128:129], v[98:99] op_sel_hi:[1,0]
	v_pk_mul_f32 v[126:127], v[126:127], v[98:99] op_sel_hi:[1,0]
	v_pk_mul_f32 v[92:93], v[92:93], v[98:99] op_sel_hi:[1,0]
	v_pk_mul_f32 v[90:91], v[90:91], v[98:99] op_sel_hi:[1,0]
	v_pk_mul_f32 v[88:89], v[88:89], v[98:99] op_sel_hi:[1,0]
	v_pk_mul_f32 v[86:87], v[86:87], v[98:99] op_sel_hi:[1,0]
	v_pk_mul_f32 v[84:85], v[84:85], v[98:99] op_sel_hi:[1,0]
	v_pk_mul_f32 v[82:83], v[82:83], v[98:99] op_sel_hi:[1,0]
	v_sub_f32_e32 v184, v184, v99
	v_sub_f32_e32 v185, v185, v99
	v_sub_f32_e32 v94, v94, v99
	v_sub_f32_e32 v95, v95, v99
	v_sub_f32_e32 v96, v96, v99
	v_sub_f32_e32 v97, v97, v99
.LBB0_726:
	v_exp_f32_e32 v98, v182
	v_exp_f32_e32 v99, v183
	v_exp_f32_e32 v100, v184
	v_exp_f32_e32 v101, v185
	v_exp_f32_e32 v94, v94
	v_exp_f32_e32 v95, v95
	v_exp_f32_e32 v96, v96
	v_exp_f32_e32 v97, v97
	v_cvt_pk_bf16_f32 v98, v98, v99
	v_cvt_pk_bf16_f32 v99, v100, v101
	v_cvt_pk_bf16_f32 v100, v94, v95
	v_cvt_pk_bf16_f32 v101, v96, v97
	v_max_f32_e32 v106, v179, v179
	v_max_f32_e32 v107, v178, v178
	v_mfma_f32_16x16x32_bf16 v[122:125], v[6:9], v[98:101], v[78:81]
	v_max_f32_e32 v8, v180, v181
	v_max_f32_e32 v78, v176, v176
	v_max_f32_e32 v9, v78, v177
	v_max_f32_e32 v7, v107, v106
	v_max3_f32 v9, v174, v175, v9
	v_max3_f32 v7, v7, v8, v9
	v_mov_b32_e32 v8, v7
	s_nop 1
	v_permlane16_swap_b32_e32 v7, v8
	v_max_f32_e32 v7, v7, v8
	v_mov_b32_e32 v8, v7
	v_mfma_f32_16x16x32_bf16 v[94:97], v[142:145], v[98:101], v[126:129]
	s_nop 0
	v_permlane32_swap_b32_e32 v7, v8
	v_mfma_f32_16x16x32_bf16 v[90:93], v[154:157], v[98:101], v[90:93]
	v_max_f32_e32 v7, v7, v8
	v_cmp_lt_f32_e32 vcc, s29, v7
	v_mfma_f32_16x16x32_bf16 v[86:89], v[158:161], v[98:101], v[86:89]
	v_mfma_f32_16x16x32_bf16 v[82:85], v[162:165], v[98:101], v[82:85]
	s_cbranch_vccz .LBB0_728
	v_max_f32_e32 v7, 0, v7
	v_exp_f32_e64 v8, -v7
	v_add_f32_e32 v44, v44, v7
	v_sub_f32_e32 v178, v178, v7
	v_sub_f32_e32 v179, v179, v7
	v_pk_mul_f32 v[104:105], v[104:105], v[8:9] op_sel_hi:[1,0]
	v_pk_mul_f32 v[102:103], v[102:103], v[8:9] op_sel_hi:[1,0]
	v_pk_mul_f32 v[76:77], v[76:77], v[8:9] op_sel_hi:[1,0]
	v_pk_mul_f32 v[74:75], v[74:75], v[8:9] op_sel_hi:[1,0]
	v_pk_mul_f32 v[72:73], v[72:73], v[8:9] op_sel_hi:[1,0]
	v_pk_mul_f32 v[70:71], v[70:71], v[8:9] op_sel_hi:[1,0]
	v_pk_mul_f32 v[68:69], v[68:69], v[8:9] op_sel_hi:[1,0]
	v_pk_mul_f32 v[66:67], v[66:67], v[8:9] op_sel_hi:[1,0]
	v_pk_mul_f32 v[64:65], v[64:65], v[8:9] op_sel_hi:[1,0]
	v_pk_mul_f32 v[62:63], v[62:63], v[8:9] op_sel_hi:[1,0]
	v_sub_f32_e32 v180, v180, v7
	v_sub_f32_e32 v181, v181, v7
	v_sub_f32_e32 v174, v174, v7
	v_sub_f32_e32 v175, v175, v7
	v_sub_f32_e32 v176, v176, v7
	v_sub_f32_e32 v177, v177, v7
.LBB0_728:
	v_exp_f32_e32 v7, v178
	v_exp_f32_e32 v8, v179
	v_exp_f32_e32 v9, v180
	v_exp_f32_e32 v79, v181
	v_exp_f32_e32 v80, v174
	v_exp_f32_e32 v81, v175
	v_exp_f32_e32 v98, v176
	v_exp_f32_e32 v99, v177
	v_cvt_pk_bf16_f32 v78, v7, v8
	v_cvt_pk_bf16_f32 v79, v9, v79
	v_mov_b32_e32 v7, v6
	v_mov_b32_e32 v8, v6
	v_mov_b32_e32 v9, v6
	v_cvt_pk_bf16_f32 v80, v80, v81
	v_cvt_pk_bf16_f32 v81, v98, v99
	s_nop 1
	v_mfma_f32_16x16x32_bf16 v[74:77], v[142:145], v[78:81], v[74:77]
	v_mfma_f32_16x16x32_bf16 v[70:73], v[154:157], v[78:81], v[70:73]
	v_mfma_f32_16x16x32_bf16 v[66:69], v[158:161], v[78:81], v[66:69]
	v_mfma_f32_16x16x32_bf16 v[62:65], v[162:165], v[78:81], v[62:65]
	v_mfma_f32_16x16x32_bf16 v[114:117], v[6:9], v[78:81], v[102:105]
	v_max_f32_e32 v78, v170, v171
	v_max_f32_e32 v79, v172, v173
	v_max_f32_e32 v81, v168, v168
	v_max_f32_e32 v80, v81, v169
	v_max3_f32 v80, v166, v167, v80
	v_max3_f32 v78, v78, v79, v80
	v_mov_b32_e32 v79, v78
	s_nop 1
	v_permlane16_swap_b32_e32 v78, v79
	v_max_f32_e32 v78, v78, v79
	v_mov_b32_e32 v79, v78
	s_nop 1
	v_permlane32_swap_b32_e32 v78, v79
	v_max_f32_e32 v78, v78, v79
	v_cmp_lt_f32_e32 vcc, s29, v78
	s_cbranch_vccz .LBB0_730
	v_max_f32_e32 v79, 0, v78
	v_exp_f32_e64 v78, -v79
	v_add_f32_e32 v45, v45, v79
	v_sub_f32_e32 v170, v170, v79
	v_sub_f32_e32 v171, v171, v79
	v_pk_mul_f32 v[140:141], v[140:141], v[78:79] op_sel_hi:[1,0]
	v_pk_mul_f32 v[138:139], v[138:139], v[78:79] op_sel_hi:[1,0]
	v_pk_mul_f32 v[152:153], v[152:153], v[78:79] op_sel_hi:[1,0]
	v_pk_mul_f32 v[150:151], v[150:151], v[78:79] op_sel_hi:[1,0]
	v_pk_mul_f32 v[148:149], v[148:149], v[78:79] op_sel_hi:[1,0]
	v_pk_mul_f32 v[146:147], v[146:147], v[78:79] op_sel_hi:[1,0]
	v_pk_mul_f32 v[136:137], v[136:137], v[78:79] op_sel_hi:[1,0]
	v_pk_mul_f32 v[134:135], v[134:135], v[78:79] op_sel_hi:[1,0]
	v_pk_mul_f32 v[132:133], v[132:133], v[78:79] op_sel_hi:[1,0]
	v_pk_mul_f32 v[130:131], v[130:131], v[78:79] op_sel_hi:[1,0]
	v_sub_f32_e32 v172, v172, v79
	v_sub_f32_e32 v173, v173, v79
	v_sub_f32_e32 v166, v166, v79
	v_sub_f32_e32 v167, v167, v79
	v_sub_f32_e32 v168, v168, v79
	v_sub_f32_e32 v169, v169, v79

.LBB0_739:
	ds_read_b128 v[142:145], v214 offset:16384
	ds_read_b128 v[146:149], v214 offset:17408
	ds_read_b128 v[150:153], v214 offset:18432
	ds_read_b128 v[154:157], v214 offset:19456
	v_xor_b32_e32 v126, 0x80000000, v42
	v_mov_b32_e32 v127, v126
	v_mov_b32_e32 v128, v126
	v_mov_b32_e32 v129, v126
	v_xor_b32_e32 v158, 0x80000000, v44
	v_xor_b32_e32 v166, 0x80000000, v45
	s_waitcnt lgkmcnt(0)
	v_mfma_f32_16x16x32_bf16 v[130:133], v[142:145], v[10:13], v[126:129]
	v_mov_b32_e32 v159, v158
	v_mov_b32_e32 v160, v158
	v_mov_b32_e32 v161, v158
	v_mfma_f32_16x16x32_bf16 v[126:129], v[150:153], v[10:13], v[126:129]
	v_mov_b32_e32 v167, v166
	v_mov_b32_e32 v168, v166
	v_mov_b32_e32 v169, v166
	v_mfma_f32_16x16x32_bf16 v[134:137], v[154:157], v[14:17], v[126:129]
	v_mfma_f32_16x16x32_bf16 v[138:141], v[146:149], v[14:17], v[130:133]
	s_nop 2
	v_xor_b32_e32 v126, 0x80000000, v43
	v_mov_b32_e32 v127, v126
	v_mov_b32_e32 v128, v126
	v_mov_b32_e32 v129, v126
	v_mfma_f32_16x16x32_bf16 v[162:165], v[142:145], v[26:29], v[158:161]
	s_nop 0
	v_mfma_f32_16x16x32_bf16 v[130:133], v[142:145], v[18:21], v[126:129]
	v_mfma_f32_16x16x32_bf16 v[158:161], v[150:153], v[26:29], v[158:161]
	v_mfma_f32_16x16x32_bf16 v[142:145], v[142:145], v[34:37], v[166:169]
	v_mfma_f32_16x16x32_bf16 v[126:129], v[150:153], v[18:21], v[126:129]
	v_mfma_f32_16x16x32_bf16 v[170:173], v[146:149], v[30:33], v[162:165]
	v_mfma_f32_16x16x32_bf16 v[162:165], v[154:157], v[30:33], v[158:161]
	v_mfma_f32_16x16x32_bf16 v[158:161], v[146:149], v[38:41], v[142:145]
	v_mfma_f32_16x16x32_bf16 v[142:145], v[150:153], v[34:37], v[166:169]
	v_mfma_f32_16x16x32_bf16 v[130:133], v[146:149], v[22:25], v[130:133]
	v_mfma_f32_16x16x32_bf16 v[126:129], v[154:157], v[22:25], v[126:129]
	v_mfma_f32_16x16x32_bf16 v[154:157], v[154:157], v[38:41], v[142:145]
	v_max_f32_e32 v7, v138, v139
	v_max_f32_e32 v8, v140, v141
	v_max_f32_e32 v174, v136, v136
	v_max_f32_e32 v9, v174, v137
	v_max3_f32 v9, v134, v135, v9
	v_max3_f32 v7, v7, v8, v9
	v_mov_b32_e32 v8, v7
	s_nop 1
	v_permlane16_swap_b32_e32 v7, v8
	ds_read_b128 v[142:145], v214 offset:20480
	ds_read_b128 v[146:149], v214 offset:21504
	ds_read_b128 v[150:153], v214 offset:22528
	ds_read_b128 v[166:169], v214 offset:23552
	v_max_f32_e32 v7, v7, v8
	v_mov_b32_e32 v8, v7
	s_nop 1
	v_permlane32_swap_b32_e32 v7, v8
	v_max_f32_e32 v7, v7, v8
	v_cmp_lt_f32_e32 vcc, s29, v7
	s_cbranch_vccz .LBB0_741
	v_max_f32_e32 v7, 0, v7
	v_exp_f32_e64 v8, -v7
	v_add_f32_e32 v42, v42, v7
	v_sub_f32_e32 v138, v138, v7
	v_sub_f32_e32 v139, v139, v7
	v_pk_mul_f32 v[120:121], v[120:121], v[8:9] op_sel_hi:[1,0]
	v_pk_mul_f32 v[118:119], v[118:119], v[8:9] op_sel_hi:[1,0]
	v_pk_mul_f32 v[60:61], v[60:61], v[8:9] op_sel_hi:[1,0]
	v_pk_mul_f32 v[58:59], v[58:59], v[8:9] op_sel_hi:[1,0]
	v_pk_mul_f32 v[56:57], v[56:57], v[8:9] op_sel_hi:[1,0]
	v_pk_mul_f32 v[54:55], v[54:55], v[8:9] op_sel_hi:[1,0]
	v_pk_mul_f32 v[52:53], v[52:53], v[8:9] op_sel_hi:[1,0]
	v_pk_mul_f32 v[50:51], v[50:51], v[8:9] op_sel_hi:[1,0]
	v_pk_mul_f32 v[48:49], v[48:49], v[8:9] op_sel_hi:[1,0]
	v_pk_mul_f32 v[46:47], v[46:47], v[8:9] op_sel_hi:[1,0]
	v_sub_f32_e32 v140, v140, v7
	v_sub_f32_e32 v141, v141, v7
	v_sub_f32_e32 v134, v134, v7
	v_sub_f32_e32 v135, v135, v7
	v_sub_f32_e32 v136, v136, v7
	v_sub_f32_e32 v137, v137, v7
.LBB0_741:
	v_exp_f32_e32 v7, v138
	v_exp_f32_e32 v8, v139
	v_exp_f32_e32 v9, v140
	v_exp_f32_e32 v138, v141
	v_exp_f32_e32 v139, v134
	v_exp_f32_e32 v140, v135
	v_exp_f32_e32 v141, v136
	v_exp_f32_e32 v137, v137
	v_cvt_pk_bf16_f32 v134, v7, v8
	v_cvt_pk_bf16_f32 v135, v9, v138
	v_mov_b32_e32 v7, v6
	v_mov_b32_e32 v8, v6
	v_mov_b32_e32 v9, v6
	v_cvt_pk_bf16_f32 v136, v139, v140
	v_cvt_pk_bf16_f32 v137, v141, v137
	s_waitcnt lgkmcnt(0)
	s_nop 0
	v_mfma_f32_16x16x32_bf16 v[58:61], v[142:145], v[134:137], v[58:61]
	v_mfma_f32_16x16x32_bf16 v[54:57], v[146:149], v[134:137], v[54:57]
	v_mfma_f32_16x16x32_bf16 v[50:53], v[150:153], v[134:137], v[50:53]
	v_mfma_f32_16x16x32_bf16 v[46:49], v[166:169], v[134:137], v[46:49]
	v_mfma_f32_16x16x32_bf16 v[118:121], v[6:9], v[134:137], v[118:121]
	v_max_f32_e32 v134, v130, v131
	v_max_f32_e32 v135, v132, v133
	v_max_f32_e32 v137, v128, v128
	v_max_f32_e32 v136, v137, v129
	v_max3_f32 v136, v126, v127, v136
	v_max3_f32 v134, v134, v135, v136
	v_mov_b32_e32 v135, v134
	s_nop 1
	v_permlane16_swap_b32_e32 v134, v135
	v_max_f32_e32 v134, v134, v135
	v_mov_b32_e32 v135, v134
	s_nop 1
	v_permlane32_swap_b32_e32 v134, v135
	v_max_f32_e32 v134, v134, v135
	v_cmp_lt_f32_e32 vcc, s29, v134
	s_cbranch_vccz .LBB0_743
	v_max_f32_e32 v135, 0, v134
	v_exp_f32_e64 v134, -v135
	v_add_f32_e32 v43, v43, v135
	v_sub_f32_e32 v130, v130, v135
	v_sub_f32_e32 v131, v131, v135
	v_pk_mul_f32 v[124:125], v[124:125], v[134:135] op_sel_hi:[1,0]
	v_pk_mul_f32 v[122:123], v[122:123], v[134:135] op_sel_hi:[1,0]
	v_pk_mul_f32 v[96:97], v[96:97], v[134:135] op_sel_hi:[1,0]
	v_pk_mul_f32 v[94:95], v[94:95], v[134:135] op_sel_hi:[1,0]
	v_pk_mul_f32 v[92:93], v[92:93], v[134:135] op_sel_hi:[1,0]
	v_pk_mul_f32 v[90:91], v[90:91], v[134:135] op_sel_hi:[1,0]
	v_pk_mul_f32 v[88:89], v[88:89], v[134:135] op_sel_hi:[1,0]
	v_pk_mul_f32 v[86:87], v[86:87], v[134:135] op_sel_hi:[1,0]
	v_pk_mul_f32 v[84:85], v[84:85], v[134:135] op_sel_hi:[1,0]
	v_pk_mul_f32 v[82:83], v[82:83], v[134:135] op_sel_hi:[1,0]
	v_sub_f32_e32 v132, v132, v135
	v_sub_f32_e32 v133, v133, v135
	v_sub_f32_e32 v126, v126, v135
	v_sub_f32_e32 v127, v127, v135
	v_sub_f32_e32 v128, v128, v135
	v_sub_f32_e32 v129, v129, v135
.LBB0_743:
	v_exp_f32_e32 v130, v130
	v_exp_f32_e32 v131, v131
	v_exp_f32_e32 v132, v132
	v_exp_f32_e32 v133, v133
	v_exp_f32_e32 v126, v126
	v_exp_f32_e32 v127, v127
	v_exp_f32_e32 v128, v128
	v_exp_f32_e32 v129, v129
	v_cvt_pk_bf16_f32 v138, v130, v131
	v_cvt_pk_bf16_f32 v139, v132, v133
	v_cvt_pk_bf16_f32 v140, v126, v127
	v_cvt_pk_bf16_f32 v141, v128, v129
	s_nop 1
	v_mfma_f32_16x16x32_bf16 v[134:137], v[142:145], v[138:141], v[94:97]
	v_mfma_f32_16x16x32_bf16 v[130:133], v[146:149], v[138:141], v[90:93]
	v_mfma_f32_16x16x32_bf16 v[126:129], v[150:153], v[138:141], v[86:89]
	v_mfma_f32_16x16x32_bf16 v[94:97], v[166:169], v[138:141], v[82:85]
	s_nop 2
	v_max_f32_e32 v83, v170, v170
	v_mfma_f32_16x16x32_bf16 v[138:141], v[6:9], v[138:141], v[122:125]
	v_max_f32_e32 v7, v83, v171
	v_max_f32_e32 v8, v172, v173
	v_max_f32_e32 v82, v164, v164
	v_max_f32_e32 v9, v82, v165
	v_max3_f32 v9, v162, v163, v9
	v_max3_f32 v7, v7, v8, v9
	v_mov_b32_e32 v8, v7
	s_nop 1
	v_permlane16_swap_b32_e32 v7, v8
	v_max_f32_e32 v7, v7, v8
	v_mov_b32_e32 v8, v7
	s_nop 1
	v_permlane32_swap_b32_e32 v7, v8
	v_max_f32_e32 v7, v7, v8
	v_cmp_lt_f32_e32 vcc, s29, v7
	s_cbranch_vccz .LBB0_745
	v_max_f32_e32 v7, 0, v7
	v_exp_f32_e64 v8, -v7
	v_add_f32_e32 v44, v44, v7
	v_sub_f32_e32 v170, v170, v7
	v_sub_f32_e32 v171, v171, v7
	v_pk_mul_f32 v[116:117], v[116:117], v[8:9] op_sel_hi:[1,0]
	v_pk_mul_f32 v[114:115], v[114:115], v[8:9] op_sel_hi:[1,0]
	v_pk_mul_f32 v[76:77], v[76:77], v[8:9] op_sel_hi:[1,0]
	v_pk_mul_f32 v[74:75], v[74:75], v[8:9] op_sel_hi:[1,0]
	v_pk_mul_f32 v[72:73], v[72:73], v[8:9] op_sel_hi:[1,0]
	v_pk_mul_f32 v[70:71], v[70:71], v[8:9] op_sel_hi:[1,0]
	v_pk_mul_f32 v[68:69], v[68:69], v[8:9] op_sel_hi:[1,0]
	v_pk_mul_f32 v[66:67], v[66:67], v[8:9] op_sel_hi:[1,0]
	v_pk_mul_f32 v[64:65], v[64:65], v[8:9] op_sel_hi:[1,0]
	v_pk_mul_f32 v[62:63], v[62:63], v[8:9] op_sel_hi:[1,0]
	v_sub_f32_e32 v172, v172, v7
	v_sub_f32_e32 v173, v173, v7
	v_sub_f32_e32 v162, v162, v7
	v_sub_f32_e32 v163, v163, v7
	v_sub_f32_e32 v164, v164, v7
	v_sub_f32_e32 v165, v165, v7
.LBB0_745:
	v_exp_f32_e32 v7, v170
	v_exp_f32_e32 v8, v171
	v_exp_f32_e32 v9, v172
	v_exp_f32_e32 v83, v173
	v_exp_f32_e32 v84, v162
	v_exp_f32_e32 v85, v163
	v_exp_f32_e32 v86, v164
	v_exp_f32_e32 v87, v165
	v_cvt_pk_bf16_f32 v82, v7, v8
	v_cvt_pk_bf16_f32 v83, v9, v83
	v_mov_b32_e32 v7, v6
	v_mov_b32_e32 v8, v6
	v_mov_b32_e32 v9, v6
	v_cvt_pk_bf16_f32 v84, v84, v85
	v_cvt_pk_bf16_f32 v85, v86, v87
	s_nop 1
	v_mfma_f32_16x16x32_bf16 v[74:77], v[142:145], v[82:85], v[74:77]
	v_mfma_f32_16x16x32_bf16 v[70:73], v[146:149], v[82:85], v[70:73]
	v_mfma_f32_16x16x32_bf16 v[66:69], v[150:153], v[82:85], v[66:69]
	v_mfma_f32_16x16x32_bf16 v[62:65], v[166:169], v[82:85], v[62:65]
	v_mfma_f32_16x16x32_bf16 v[162:165], v[6:9], v[82:85], v[114:117]
	v_max_f32_e32 v82, v158, v159
	v_max_f32_e32 v83, v160, v161
	v_max_f32_e32 v85, v156, v156
	v_max_f32_e32 v84, v85, v157
	v_max3_f32 v84, v154, v155, v84
	v_max3_f32 v82, v82, v83, v84
	v_mov_b32_e32 v83, v82
	s_nop 1
	v_permlane16_swap_b32_e32 v82, v83
	v_max_f32_e32 v82, v82, v83
	v_mov_b32_e32 v83, v82
	s_nop 1
	v_permlane32_swap_b32_e32 v82, v83
	v_max_f32_e32 v82, v82, v83
	v_cmp_lt_f32_e32 vcc, s29, v82
	s_cbranch_vccz .LBB0_747
	v_max_f32_e32 v83, 0, v82
	v_exp_f32_e64 v82, -v83
	v_add_f32_e32 v45, v45, v83
	v_sub_f32_e32 v158, v158, v83
	v_sub_f32_e32 v159, v159, v83
	v_pk_mul_f32 v[112:113], v[112:113], v[82:83] op_sel_hi:[1,0]
	v_pk_mul_f32 v[110:111], v[110:111], v[82:83] op_sel_hi:[1,0]
	v_pk_mul_f32 v[108:109], v[108:109], v[82:83] op_sel_hi:[1,0]
	v_pk_mul_f32 v[106:107], v[106:107], v[82:83] op_sel_hi:[1,0]
	v_pk_mul_f32 v[104:105], v[104:105], v[82:83] op_sel_hi:[1,0]
	v_pk_mul_f32 v[102:103], v[102:103], v[82:83] op_sel_hi:[1,0]
	v_pk_mul_f32 v[100:101], v[100:101], v[82:83] op_sel_hi:[1,0]
	v_pk_mul_f32 v[98:99], v[98:99], v[82:83] op_sel_hi:[1,0]
	v_pk_mul_f32 v[80:81], v[80:81], v[82:83] op_sel_hi:[1,0]
	v_pk_mul_f32 v[78:79], v[78:79], v[82:83] op_sel_hi:[1,0]
	v_sub_f32_e32 v160, v160, v83
	v_sub_f32_e32 v161, v161, v83
	v_sub_f32_e32 v154, v154, v83
	v_sub_f32_e32 v155, v155, v83
	v_sub_f32_e32 v156, v156, v83
	v_sub_f32_e32 v157, v157, v83

.LBB0_756:
	ds_read_b128 v[98:101], v214 offset:24576
	ds_read_b128 v[106:109], v214 offset:25600
	ds_read_b128 v[110:113], v214 offset:26624
	ds_read_b128 v[114:117], v214 offset:27648
	v_xor_b32_e32 v78, 0x80000000, v42
	v_xor_b32_e32 v102, 0x80000000, v44
	v_mov_b32_e32 v79, v78
	v_mov_b32_e32 v80, v78
	v_mov_b32_e32 v81, v78
	v_mov_b32_e32 v103, v102
	v_mov_b32_e32 v104, v102
	v_mov_b32_e32 v105, v102
	s_waitcnt lgkmcnt(0)
	v_mfma_f32_16x16x32_bf16 v[82:85], v[98:101], v[10:13], v[78:81]
	v_mfma_f32_16x16x32_bf16 v[78:81], v[110:113], v[10:13], v[78:81]
	v_mfma_f32_16x16x32_bf16 v[122:125], v[98:101], v[26:29], v[102:105]
	v_mfma_f32_16x16x32_bf16 v[86:89], v[114:117], v[14:17], v[78:81]
	s_nop 5
	v_xor_b32_e32 v78, 0x80000000, v43
	v_mfma_f32_16x16x32_bf16 v[190:193], v[106:109], v[30:33], v[122:125]
	v_mov_b32_e32 v79, v78
	v_mov_b32_e32 v80, v78
	v_mov_b32_e32 v81, v78
	v_xor_b32_e32 v122, 0x80000000, v45
	v_mov_b32_e32 v123, v122
	v_mov_b32_e32 v124, v122
	v_mov_b32_e32 v125, v122
	v_mfma_f32_16x16x32_bf16 v[90:93], v[106:109], v[14:17], v[82:85]
	v_mfma_f32_16x16x32_bf16 v[82:85], v[98:101], v[18:21], v[78:81]
	v_mfma_f32_16x16x32_bf16 v[98:101], v[98:101], v[34:37], v[122:125]
	v_mfma_f32_16x16x32_bf16 v[78:81], v[110:113], v[18:21], v[78:81]
	v_mfma_f32_16x16x32_bf16 v[102:105], v[110:113], v[26:29], v[102:105]
	v_mfma_f32_16x16x32_bf16 v[186:189], v[106:109], v[38:41], v[98:101]
	v_mfma_f32_16x16x32_bf16 v[98:101], v[110:113], v[34:37], v[122:125]
	v_mfma_f32_16x16x32_bf16 v[82:85], v[106:109], v[22:25], v[82:85]
	v_mfma_f32_16x16x32_bf16 v[78:81], v[114:117], v[22:25], v[78:81]
	v_mfma_f32_16x16x32_bf16 v[102:105], v[114:117], v[30:33], v[102:105]
	v_mfma_f32_16x16x32_bf16 v[182:185], v[114:117], v[38:41], v[98:101]
	v_max_f32_e32 v7, v90, v91
	v_max_f32_e32 v8, v92, v93
	s_nop 1
	v_max_f32_e32 v98, v88, v88
	v_max_f32_e32 v9, v98, v89
	v_max3_f32 v9, v86, v87, v9
	v_max3_f32 v7, v7, v8, v9
	v_mov_b32_e32 v8, v7
	s_nop 1
	v_permlane16_swap_b32_e32 v7, v8
	ds_read_b128 v[166:169], v214 offset:28672
	ds_read_b128 v[170:173], v214 offset:29696
	ds_read_b128 v[174:177], v214 offset:30720
	ds_read_b128 v[178:181], v214 offset:31744
	v_max_f32_e32 v7, v7, v8
	v_mov_b32_e32 v8, v7
	s_nop 1
	v_permlane32_swap_b32_e32 v7, v8
	v_max_f32_e32 v7, v7, v8
	v_cmp_lt_f32_e32 vcc, s29, v7
	s_cbranch_vccz .LBB0_758
	v_max_f32_e32 v7, 0, v7
	v_exp_f32_e64 v8, -v7
	v_add_f32_e32 v42, v42, v7
	v_sub_f32_e32 v90, v90, v7
	v_sub_f32_e32 v91, v91, v7
	v_pk_mul_f32 v[120:121], v[120:121], v[8:9] op_sel_hi:[1,0]
	v_pk_mul_f32 v[118:119], v[118:119], v[8:9] op_sel_hi:[1,0]
	v_pk_mul_f32 v[60:61], v[60:61], v[8:9] op_sel_hi:[1,0]
	v_pk_mul_f32 v[58:59], v[58:59], v[8:9] op_sel_hi:[1,0]
	v_pk_mul_f32 v[56:57], v[56:57], v[8:9] op_sel_hi:[1,0]
	v_pk_mul_f32 v[54:55], v[54:55], v[8:9] op_sel_hi:[1,0]
	v_pk_mul_f32 v[52:53], v[52:53], v[8:9] op_sel_hi:[1,0]
	v_pk_mul_f32 v[50:51], v[50:51], v[8:9] op_sel_hi:[1,0]
	v_pk_mul_f32 v[48:49], v[48:49], v[8:9] op_sel_hi:[1,0]
	v_pk_mul_f32 v[46:47], v[46:47], v[8:9] op_sel_hi:[1,0]
	v_sub_f32_e32 v92, v92, v7
	v_sub_f32_e32 v93, v93, v7
	v_sub_f32_e32 v86, v86, v7
	v_sub_f32_e32 v87, v87, v7
	v_sub_f32_e32 v88, v88, v7
	v_sub_f32_e32 v89, v89, v7
.LBB0_758:
	v_exp_f32_e32 v7, v90
	v_exp_f32_e32 v8, v91
	v_exp_f32_e32 v9, v92
	v_exp_f32_e32 v90, v93
	v_exp_f32_e32 v91, v86
	v_exp_f32_e32 v92, v87
	v_exp_f32_e32 v93, v88
	v_exp_f32_e32 v89, v89
	v_cvt_pk_bf16_f32 v86, v7, v8
	v_cvt_pk_bf16_f32 v87, v9, v90
	v_cvt_pk_bf16_f32 v88, v91, v92
	v_cvt_pk_bf16_f32 v89, v93, v89
	v_mov_b32_e32 v7, v6
	v_mov_b32_e32 v8, v6
	s_waitcnt lgkmcnt(0)
	v_mfma_f32_16x16x32_bf16 v[98:101], v[178:181], v[86:89], v[46:49]
	v_mov_b32_e32 v9, v6
	s_nop 1
	v_max_f32_e32 v46, v82, v83
	v_max_f32_e32 v47, v84, v85
	v_max_f32_e32 v49, v80, v80
	v_max_f32_e32 v48, v49, v81
	v_max3_f32 v48, v78, v79, v48
	v_max3_f32 v46, v46, v47, v48
	v_mov_b32_e32 v47, v46
	s_nop 1
	v_permlane16_swap_b32_e32 v46, v47
	v_max_f32_e32 v46, v46, v47
	v_mov_b32_e32 v47, v46
	v_mfma_f32_16x16x32_bf16 v[114:117], v[166:169], v[86:89], v[58:61]
	s_nop 0
	v_permlane32_swap_b32_e32 v46, v47
	v_mfma_f32_16x16x32_bf16 v[110:113], v[170:173], v[86:89], v[54:57]
	v_max_f32_e32 v46, v46, v47
	v_cmp_lt_f32_e32 vcc, s29, v46
	v_mfma_f32_16x16x32_bf16 v[106:109], v[174:177], v[86:89], v[50:53]
	v_mfma_f32_16x16x32_bf16 v[122:125], v[6:9], v[86:89], v[118:121]
	s_cbranch_vccz .LBB0_760
	v_max_f32_e32 v47, 0, v46
	v_exp_f32_e64 v46, -v47
	v_add_f32_e32 v43, v43, v47
	v_sub_f32_e32 v82, v82, v47
	v_sub_f32_e32 v83, v83, v47
	v_pk_mul_f32 v[140:141], v[140:141], v[46:47] op_sel_hi:[1,0]
	v_pk_mul_f32 v[138:139], v[138:139], v[46:47] op_sel_hi:[1,0]
	v_pk_mul_f32 v[136:137], v[136:137], v[46:47] op_sel_hi:[1,0]
	v_pk_mul_f32 v[134:135], v[134:135], v[46:47] op_sel_hi:[1,0]
	v_pk_mul_f32 v[132:133], v[132:133], v[46:47] op_sel_hi:[1,0]
	v_pk_mul_f32 v[130:131], v[130:131], v[46:47] op_sel_hi:[1,0]
	v_pk_mul_f32 v[128:129], v[128:129], v[46:47] op_sel_hi:[1,0]
	v_pk_mul_f32 v[126:127], v[126:127], v[46:47] op_sel_hi:[1,0]
	v_pk_mul_f32 v[96:97], v[96:97], v[46:47] op_sel_hi:[1,0]
	v_pk_mul_f32 v[94:95], v[94:95], v[46:47] op_sel_hi:[1,0]
	v_sub_f32_e32 v84, v84, v47
	v_sub_f32_e32 v85, v85, v47
	v_sub_f32_e32 v78, v78, v47
	v_sub_f32_e32 v79, v79, v47
	v_sub_f32_e32 v80, v80, v47
	v_sub_f32_e32 v81, v81, v47
.LBB0_760:
	v_exp_f32_e32 v46, v82
	v_exp_f32_e32 v47, v83
	v_exp_f32_e32 v48, v84
	v_exp_f32_e32 v49, v85
	v_exp_f32_e32 v50, v78
	v_exp_f32_e32 v51, v79
	v_exp_f32_e32 v52, v80
	v_exp_f32_e32 v53, v81
	v_cvt_pk_bf16_f32 v46, v46, v47
	v_cvt_pk_bf16_f32 v47, v48, v49
	v_cvt_pk_bf16_f32 v48, v50, v51
	v_cvt_pk_bf16_f32 v49, v52, v53
	v_max_f32_e32 v50, v191, v191
	v_max_f32_e32 v51, v190, v190
	v_mfma_f32_16x16x32_bf16 v[118:121], v[6:9], v[46:49], v[138:141]
	v_max_f32_e32 v8, v192, v193
	v_mfma_f32_16x16x32_bf16 v[90:93], v[166:169], v[46:49], v[134:137]
	v_max_f32_e32 v7, v51, v50
	v_mfma_f32_16x16x32_bf16 v[86:89], v[170:173], v[46:49], v[130:133]
	v_mfma_f32_16x16x32_bf16 v[82:85], v[174:177], v[46:49], v[126:129]
	v_mfma_f32_16x16x32_bf16 v[78:81], v[178:181], v[46:49], v[94:97]
	v_max_f32_e32 v46, v104, v104
	v_max_f32_e32 v9, v46, v105
	v_max3_f32 v9, v102, v103, v9
	v_max3_f32 v7, v7, v8, v9
	v_mov_b32_e32 v8, v7
	s_nop 1
	v_permlane16_swap_b32_e32 v7, v8
	v_max_f32_e32 v7, v7, v8
	v_mov_b32_e32 v8, v7
	s_nop 1
	v_permlane32_swap_b32_e32 v7, v8
	v_max_f32_e32 v7, v7, v8
	v_cmp_lt_f32_e32 vcc, s29, v7
	s_cbranch_vccz .LBB0_762
	v_max_f32_e32 v7, 0, v7
	v_exp_f32_e64 v8, -v7
	v_add_f32_e32 v44, v44, v7
	v_sub_f32_e32 v190, v190, v7
	v_sub_f32_e32 v191, v191, v7
	v_pk_mul_f32 v[164:165], v[164:165], v[8:9] op_sel_hi:[1,0]
	v_pk_mul_f32 v[162:163], v[162:163], v[8:9] op_sel_hi:[1,0]
	v_pk_mul_f32 v[76:77], v[76:77], v[8:9] op_sel_hi:[1,0]
	v_pk_mul_f32 v[74:75], v[74:75], v[8:9] op_sel_hi:[1,0]
	v_pk_mul_f32 v[72:73], v[72:73], v[8:9] op_sel_hi:[1,0]
	v_pk_mul_f32 v[70:71], v[70:71], v[8:9] op_sel_hi:[1,0]
	v_pk_mul_f32 v[68:69], v[68:69], v[8:9] op_sel_hi:[1,0]
	v_pk_mul_f32 v[66:67], v[66:67], v[8:9] op_sel_hi:[1,0]
	v_pk_mul_f32 v[64:65], v[64:65], v[8:9] op_sel_hi:[1,0]
	v_pk_mul_f32 v[62:63], v[62:63], v[8:9] op_sel_hi:[1,0]
	v_sub_f32_e32 v192, v192, v7
	v_sub_f32_e32 v193, v193, v7
	v_sub_f32_e32 v102, v102, v7
	v_sub_f32_e32 v103, v103, v7
	v_sub_f32_e32 v104, v104, v7
	v_sub_f32_e32 v105, v105, v7
.LBB0_762:
	v_exp_f32_e32 v7, v190
	v_exp_f32_e32 v8, v191
	v_exp_f32_e32 v9, v192
	v_exp_f32_e32 v47, v193
	v_exp_f32_e32 v48, v102
	v_exp_f32_e32 v49, v103
	v_exp_f32_e32 v50, v104
	v_exp_f32_e32 v51, v105
	v_cvt_pk_bf16_f32 v46, v7, v8
	v_cvt_pk_bf16_f32 v47, v9, v47
	v_mov_b32_e32 v7, v6
	v_mov_b32_e32 v8, v6
	v_mov_b32_e32 v9, v6
	v_cvt_pk_bf16_f32 v48, v48, v49
	v_cvt_pk_bf16_f32 v49, v50, v51
	s_nop 1
	v_mfma_f32_16x16x32_bf16 v[74:77], v[166:169], v[46:49], v[74:77]
	v_mfma_f32_16x16x32_bf16 v[70:73], v[170:173], v[46:49], v[70:73]
	v_mfma_f32_16x16x32_bf16 v[66:69], v[174:177], v[46:49], v[66:69]
	v_mfma_f32_16x16x32_bf16 v[62:65], v[178:181], v[46:49], v[62:65]
	v_mfma_f32_16x16x32_bf16 v[102:105], v[6:9], v[46:49], v[162:165]
	v_max_f32_e32 v46, v186, v187
	v_max_f32_e32 v47, v188, v189
	v_max_f32_e32 v49, v184, v184
	v_max_f32_e32 v48, v49, v185
	v_max3_f32 v48, v182, v183, v48
	v_max3_f32 v46, v46, v47, v48
	v_mov_b32_e32 v47, v46
	s_nop 1
	v_permlane16_swap_b32_e32 v46, v47
	v_max_f32_e32 v46, v46, v47
	v_mov_b32_e32 v47, v46
	s_nop 1
	v_permlane32_swap_b32_e32 v46, v47
	v_max_f32_e32 v46, v46, v47
	v_cmp_lt_f32_e32 vcc, s29, v46
	s_cbranch_vccz .LBB0_693
	v_max_f32_e32 v47, 0, v46
	v_exp_f32_e64 v46, -v47
	v_add_f32_e32 v45, v45, v47
	v_sub_f32_e32 v186, v186, v47
	v_sub_f32_e32 v187, v187, v47
	v_pk_mul_f32 v[144:145], v[144:145], v[46:47] op_sel_hi:[1,0]
	v_pk_mul_f32 v[142:143], v[142:143], v[46:47] op_sel_hi:[1,0]
	v_pk_mul_f32 v[160:161], v[160:161], v[46:47] op_sel_hi:[1,0]
	v_pk_mul_f32 v[158:159], v[158:159], v[46:47] op_sel_hi:[1,0]
	v_pk_mul_f32 v[156:157], v[156:157], v[46:47] op_sel_hi:[1,0]
	v_pk_mul_f32 v[154:155], v[154:155], v[46:47] op_sel_hi:[1,0]
	v_pk_mul_f32 v[152:153], v[152:153], v[46:47] op_sel_hi:[1,0]
	v_pk_mul_f32 v[150:151], v[150:151], v[46:47] op_sel_hi:[1,0]
	v_pk_mul_f32 v[148:149], v[148:149], v[46:47] op_sel_hi:[1,0]
	v_pk_mul_f32 v[146:147], v[146:147], v[46:47] op_sel_hi:[1,0]
	v_sub_f32_e32 v188, v188, v47
	v_sub_f32_e32 v189, v189, v47
	v_sub_f32_e32 v182, v182, v47
	v_sub_f32_e32 v183, v183, v47
	v_sub_f32_e32 v184, v184, v47
	v_sub_f32_e32 v185, v185, v47
	s_branch .LBB0_693

.LBB0_797:
	s_add_i32 s58, s35, -6
	s_cmp_lt_u32 s58, 32
	s_cselect_b64 s[14:15], -1, 0
	s_and_b64 s[26:27], s[14:15], exec
	s_cselect_b32 s26, 0, 0xffffffe0
	s_add_i32 s26, s26, s35
	s_add_i32 s26, s26, -3
	s_lshl_b32 s33, s26, 5
	s_lshl_b32 s26, s26, 15
	s_and_b32 s26, s26, 0x7ffc0000
	s_and_b32 s27, s33, 0xe0
	s_or_b32 s26, s26, s27
	s_lshl_b32 s52, s26, 1
	s_and_b64 s[26:27], s[14:15], exec
	s_mul_i32 s26, s11, s33
	s_mul_hi_u32 s27, s10, s33
	s_cselect_b32 s53, s65, s23
	s_cselect_b32 s54, s64, s22
	s_add_i32 s55, s27, s26
	s_mul_i32 s59, s10, s33
	s_and_b64 s[26:27], s[36:37], exec
	s_cselect_b32 s26, s52, s59
	s_cselect_b32 s27, 0, s55
	s_add_u32 s26, s54, s26
	s_addc_u32 s27, s53, s27
	v_lshl_add_u64 v[8:9], s[26:27], 0, v[2:3]
	s_and_b64 s[26:27], s[14:15], exec
	s_mul_i32 s26, s21, s33
	s_mul_hi_u32 s27, s20, s33
	s_cselect_b32 s53, s17, s71
	s_cselect_b32 s54, s16, s19
	s_add_i32 s55, s27, s26
	s_mul_i32 s59, s20, s33
	s_and_b64 s[26:27], s[74:75], exec
	s_cselect_b32 s26, s52, s59
	s_cselect_b32 s27, 0, s55
	s_add_u32 s26, s54, s26
	s_addc_u32 s27, s53, s27
	s_waitcnt vmcnt(3)
	s_and_b64 s[14:15], s[14:15], exec
	s_mov_b32 m0, s93
	s_waitcnt lgkmcnt(0)
	s_barrier
	s_mul_i32 s14, s45, s33
	s_mul_hi_u32 s15, s44, s33
	global_load_lds_dwordx4 v[8:9], off
	v_lshl_add_u64 v[8:9], s[26:27], 0, v[124:125]
	s_cselect_b32 s26, s25, s51
	s_cselect_b32 s27, s24, s50
	s_add_i32 s53, s15, s14
	s_mul_i32 s33, s44, s33
	s_and_b64 s[14:15], s[86:87], exec
	s_cselect_b32 s14, s52, s33
	s_cselect_b32 s15, 0, s53
	s_add_u32 s14, s27, s14
	s_mov_b32 m0, s79
	s_addc_u32 s15, s26, s15
	global_load_lds_dwordx4 v[8:9], off
	v_lshl_add_u64 v[8:9], s[14:15], 0, v[126:127]
	s_mov_b32 m0, s38
	v_xor_b32_e32 v86, 0x80000000, v119
	global_load_lds_dwordx4 v[8:9], off
	ds_read_b128 v[172:175], v150 offset:24576
	ds_read_b128 v[176:179], v150 offset:25600
	ds_read_b128 v[180:183], v150 offset:26624
	ds_read_b128 v[184:187], v150 offset:27648
	ds_read_b128 v[188:191], v150 offset:28672
	ds_read_b128 v[212:215], v150 offset:29696
	ds_read_b128 v[216:219], v150 offset:30720
	ds_read_b128 v[220:223], v150 offset:31744
	v_mov_b32_e32 v87, v86
	v_mov_b32_e32 v88, v86
	v_mov_b32_e32 v89, v86
	s_waitcnt lgkmcnt(7)
	s_nop 0
	v_mfma_f32_16x16x32_bf16 v[42:45], v[172:175], v[10:13], v[86:89]
	ds_read_b128 v[172:175], v150 offset:32768
	v_max_f32_e32 v7, v34, v35
	s_waitcnt lgkmcnt(7)
	v_mfma_f32_16x16x32_bf16 v[42:45], v[176:179], v[14:17], v[42:45]
	ds_read_b128 v[176:179], v150 offset:33792
	v_max_f32_e32 v8, v36, v37
	s_waitcnt lgkmcnt(7)
	v_mfma_f32_16x16x32_bf16 v[42:45], v[180:183], v[18:21], v[42:45]
	ds_read_b128 v[180:183], v150 offset:34816
	v_max_f32_e32 v121, v40, v40
	s_waitcnt lgkmcnt(7)
	v_mfma_f32_16x16x32_bf16 v[42:45], v[184:187], v[22:25], v[42:45]
	ds_read_b128 v[184:187], v150 offset:35840
	v_max_f32_e32 v9, v121, v41
	v_max3_f32 v9, v38, v39, v9
	s_waitcnt lgkmcnt(7)
	v_mfma_f32_16x16x32_bf16 v[42:45], v[188:191], v[26:29], v[42:45]
	v_max3_f32 v7, v7, v8, v9
	v_mov_b32_e32 v8, v7
	s_waitcnt lgkmcnt(6)
	v_mfma_f32_16x16x32_bf16 v[42:45], v[212:215], v[30:33], v[42:45]
	v_permlane16_swap_b32_e32 v7, v8
	s_waitcnt lgkmcnt(5)
	v_mfma_f32_16x16x32_bf16 v[86:89], v[216:219], v[10:13], v[86:89]
	s_waitcnt lgkmcnt(4)
	v_mfma_f32_16x16x32_bf16 v[46:49], v[220:223], v[14:17], v[86:89]
	v_max_f32_e32 v7, v7, v8
	s_nop 1
	v_mov_b32_e32 v8, v7
	s_waitcnt lgkmcnt(3)
	v_mfma_f32_16x16x32_bf16 v[46:49], v[172:175], v[18:21], v[46:49]
	v_permlane32_swap_b32_e32 v7, v8
	s_waitcnt lgkmcnt(2)
	v_mfma_f32_16x16x32_bf16 v[46:49], v[176:179], v[22:25], v[46:49]
	s_waitcnt lgkmcnt(1)
	v_mfma_f32_16x16x32_bf16 v[46:49], v[180:183], v[26:29], v[46:49]
	v_max_f32_e32 v7, v7, v8
	s_and_b64 vcc, exec, s[12:13]
	s_waitcnt lgkmcnt(0)
	v_mfma_f32_16x16x32_bf16 v[46:49], v[184:187], v[30:33], v[46:49]
	ds_read_b128 v[86:89], v150 offset:12288
	ds_read_b128 v[90:93], v150 offset:13312
	ds_read_b128 v[94:97], v150 offset:14336
	ds_read_b128 v[98:101], v150 offset:15360
	ds_read_b128 v[102:105], v150 offset:16384
	ds_read_b128 v[106:109], v150 offset:17408
	ds_read_b128 v[110:113], v150 offset:18432
	ds_read_b128 v[114:117], v150 offset:19456
	s_cbranch_vccnz .LBB0_800
	v_cmp_lt_f32_e32 vcc, s29, v7
	s_cbranch_vccz .LBB0_825
	v_max_f32_e32 v7, 0, v7

.LBB0_804:
	v_xor_b32_e32 v168, 0x80000000, v119
	ds_read_b128 v[34:37], v150 offset:49152
	ds_read_b128 v[38:41], v150 offset:50176
	ds_read_b128 v[86:89], v150 offset:51200
	ds_read_b128 v[90:93], v150 offset:52224
	ds_read_b128 v[94:97], v150 offset:53248
	ds_read_b128 v[98:101], v150 offset:54272
	ds_read_b128 v[102:105], v150 offset:55296
	ds_read_b128 v[106:109], v150 offset:56320
	ds_read_b128 v[110:113], v150 offset:57344
	ds_read_b128 v[114:117], v150 offset:58368
	ds_read_b128 v[160:163], v150 offset:59392
	ds_read_b128 v[164:167], v150 offset:60416
	v_mov_b32_e32 v169, v168
	v_mov_b32_e32 v170, v168
	v_mov_b32_e32 v171, v168
	s_waitcnt lgkmcnt(0)
	s_nop 1
	v_mfma_f32_16x16x32_bf16 v[34:37], v[34:37], v[10:13], v[168:171]
	v_max_f32_e32 v7, v42, v43
	v_mfma_f32_16x16x32_bf16 v[34:37], v[38:41], v[14:17], v[34:37]
	v_max_f32_e32 v8, v44, v45
	v_max_f32_e32 v121, v48, v48
	v_mfma_f32_16x16x32_bf16 v[38:41], v[102:105], v[10:13], v[168:171]
	v_max_f32_e32 v9, v121, v49
	v_max3_f32 v9, v46, v47, v9
	v_max3_f32 v7, v7, v8, v9
	v_mfma_f32_16x16x32_bf16 v[34:37], v[86:89], v[18:21], v[34:37]
	v_mov_b32_e32 v8, v7
	s_nop 1
	v_permlane16_swap_b32_e32 v7, v8
	v_mfma_f32_16x16x32_bf16 v[38:41], v[106:109], v[14:17], v[38:41]
	v_max_f32_e32 v7, v7, v8
	v_mfma_f32_16x16x32_bf16 v[34:37], v[90:93], v[22:25], v[34:37]
	v_mov_b32_e32 v8, v7
	s_nop 1
	v_permlane32_swap_b32_e32 v7, v8
	v_mfma_f32_16x16x32_bf16 v[38:41], v[110:113], v[18:21], v[38:41]
	v_max_f32_e32 v7, v7, v8
	v_mfma_f32_16x16x32_bf16 v[34:37], v[94:97], v[26:29], v[34:37]
	v_cmp_lt_f32_e32 vcc, s29, v7
	v_mfma_f32_16x16x32_bf16 v[38:41], v[114:117], v[22:25], v[38:41]
	v_mfma_f32_16x16x32_bf16 v[34:37], v[98:101], v[30:33], v[34:37]
	ds_read_b128 v[86:89], v150 offset:36864
	ds_read_b128 v[90:93], v150 offset:37888
	ds_read_b128 v[94:97], v150 offset:38912
	ds_read_b128 v[98:101], v150 offset:39936
	ds_read_b128 v[102:105], v150 offset:40960
	ds_read_b128 v[106:109], v150 offset:41984
	ds_read_b128 v[110:113], v150 offset:43008
	ds_read_b128 v[114:117], v150 offset:44032
	v_mfma_f32_16x16x32_bf16 v[38:41], v[160:163], v[26:29], v[38:41]
	v_mfma_f32_16x16x32_bf16 v[38:41], v[164:167], v[30:33], v[38:41]
	s_cbranch_vccz .LBB0_806
	v_max_f32_e32 v7, 0, v7
	v_exp_f32_e64 v8, -v7
	v_add_f32_e32 v119, v119, v7
	v_sub_f32_e32 v42, v42, v7
	v_sub_f32_e32 v43, v43, v7
	v_pk_mul_f32 v[80:81], v[80:81], v[8:9] op_sel_hi:[1,0]
	v_pk_mul_f32 v[78:79], v[78:79], v[8:9] op_sel_hi:[1,0]
	v_pk_mul_f32 v[76:77], v[76:77], v[8:9] op_sel_hi:[1,0]
	v_pk_mul_f32 v[74:75], v[74:75], v[8:9] op_sel_hi:[1,0]
	v_pk_mul_f32 v[72:73], v[72:73], v[8:9] op_sel_hi:[1,0]
	v_pk_mul_f32 v[70:71], v[70:71], v[8:9] op_sel_hi:[1,0]
	v_pk_mul_f32 v[68:69], v[68:69], v[8:9] op_sel_hi:[1,0]
	v_pk_mul_f32 v[66:67], v[66:67], v[8:9] op_sel_hi:[1,0]
	v_pk_mul_f32 v[64:65], v[64:65], v[8:9] op_sel_hi:[1,0]
	v_pk_mul_f32 v[62:63], v[62:63], v[8:9] op_sel_hi:[1,0]
	v_pk_mul_f32 v[60:61], v[60:61], v[8:9] op_sel_hi:[1,0]
	v_pk_mul_f32 v[58:59], v[58:59], v[8:9] op_sel_hi:[1,0]
	v_pk_mul_f32 v[56:57], v[56:57], v[8:9] op_sel_hi:[1,0]
	v_pk_mul_f32 v[54:55], v[54:55], v[8:9] op_sel_hi:[1,0]
	v_pk_mul_f32 v[52:53], v[52:53], v[8:9] op_sel_hi:[1,0]
	v_pk_mul_f32 v[50:51], v[50:51], v[8:9] op_sel_hi:[1,0]
	v_sub_f32_e32 v44, v44, v7
	v_sub_f32_e32 v45, v45, v7
	v_sub_f32_e32 v37, v37, v7
	v_sub_f32_e32 v36, v36, v7
	v_sub_f32_e32 v35, v35, v7
	v_sub_f32_e32 v34, v34, v7
	v_sub_f32_e32 v46, v46, v7
	v_sub_f32_e32 v47, v47, v7
	v_sub_f32_e32 v48, v48, v7
	v_sub_f32_e32 v49, v49, v7
	v_sub_f32_e32 v41, v41, v7
	v_sub_f32_e32 v40, v40, v7
	v_sub_f32_e32 v39, v39, v7
	v_sub_f32_e32 v38, v38, v7
	v_pk_mul_f32 v[84:85], v[84:85], v[8:9] op_sel_hi:[1,0]
	v_pk_mul_f32 v[82:83], v[82:83], v[8:9] op_sel_hi:[1,0]

.LBB0_812:
	v_xor_b32_e32 v168, 0x80000000, v119
	ds_read_b128 v[42:45], v135
	ds_read_b128 v[46:49], v136
	ds_read_b128 v[86:89], v137
	ds_read_b128 v[90:93], v138
	ds_read_b128 v[94:97], v139
	ds_read_b128 v[98:101], v140
	ds_read_b128 v[102:105], v141
	ds_read_b128 v[106:109], v142
	ds_read_b128 v[110:113], v143
	ds_read_b128 v[114:117], v144
	ds_read_b128 v[160:163], v145
	ds_read_b128 v[164:167], v146
	v_mov_b32_e32 v169, v168
	v_mov_b32_e32 v170, v168
	v_mov_b32_e32 v171, v168
	s_waitcnt lgkmcnt(0)
	s_nop 1
	v_mfma_f32_16x16x32_bf16 v[42:45], v[42:45], v[10:13], v[168:171]
	v_max_f32_e32 v7, v34, v35
	v_mfma_f32_16x16x32_bf16 v[42:45], v[46:49], v[14:17], v[42:45]
	v_max_f32_e32 v8, v36, v37
	v_max_f32_e32 v121, v40, v40
	v_mfma_f32_16x16x32_bf16 v[46:49], v[102:105], v[10:13], v[168:171]
	v_max_f32_e32 v9, v121, v41
	v_max3_f32 v9, v38, v39, v9
	v_max3_f32 v7, v7, v8, v9
	v_mfma_f32_16x16x32_bf16 v[42:45], v[86:89], v[18:21], v[42:45]
	v_mov_b32_e32 v8, v7
	s_nop 1
	v_permlane16_swap_b32_e32 v7, v8
	v_mfma_f32_16x16x32_bf16 v[46:49], v[106:109], v[14:17], v[46:49]
	v_max_f32_e32 v7, v7, v8
	v_mfma_f32_16x16x32_bf16 v[42:45], v[90:93], v[22:25], v[42:45]
	v_mov_b32_e32 v8, v7
	s_nop 1
	v_permlane32_swap_b32_e32 v7, v8
	v_mfma_f32_16x16x32_bf16 v[46:49], v[110:113], v[18:21], v[46:49]
	v_max_f32_e32 v7, v7, v8
	v_mfma_f32_16x16x32_bf16 v[42:45], v[94:97], v[26:29], v[42:45]
	v_cmp_lt_f32_e32 vcc, s29, v7
	v_mfma_f32_16x16x32_bf16 v[46:49], v[114:117], v[22:25], v[46:49]
	v_mfma_f32_16x16x32_bf16 v[42:45], v[98:101], v[30:33], v[42:45]
	ds_read_b128 v[86:89], v150 offset:61440
	ds_read_b128 v[90:93], v150 offset:62464
	ds_read_b128 v[94:97], v150 offset:63488
	ds_read_b128 v[98:101], v150 offset:64512
	ds_read_b128 v[102:105], v147
	ds_read_b128 v[106:109], v148
	ds_read_b128 v[110:113], v149
	ds_read_b128 v[114:117], v151
	v_mfma_f32_16x16x32_bf16 v[46:49], v[160:163], v[26:29], v[46:49]
	v_mfma_f32_16x16x32_bf16 v[46:49], v[164:167], v[30:33], v[46:49]
	s_cbranch_vccz .LBB0_814
	v_max_f32_e32 v7, 0, v7
	v_exp_f32_e64 v8, -v7
	v_add_f32_e32 v119, v119, v7
	v_sub_f32_e32 v37, v37, v7
	v_sub_f32_e32 v36, v36, v7
	v_pk_mul_f32 v[80:81], v[80:81], v[8:9] op_sel_hi:[1,0]
	v_pk_mul_f32 v[78:79], v[78:79], v[8:9] op_sel_hi:[1,0]
	v_pk_mul_f32 v[76:77], v[76:77], v[8:9] op_sel_hi:[1,0]
	v_pk_mul_f32 v[74:75], v[74:75], v[8:9] op_sel_hi:[1,0]
	v_pk_mul_f32 v[72:73], v[72:73], v[8:9] op_sel_hi:[1,0]
	v_pk_mul_f32 v[70:71], v[70:71], v[8:9] op_sel_hi:[1,0]
	v_pk_mul_f32 v[68:69], v[68:69], v[8:9] op_sel_hi:[1,0]
	v_pk_mul_f32 v[66:67], v[66:67], v[8:9] op_sel_hi:[1,0]
	v_pk_mul_f32 v[64:65], v[64:65], v[8:9] op_sel_hi:[1,0]
	v_pk_mul_f32 v[62:63], v[62:63], v[8:9] op_sel_hi:[1,0]
	v_pk_mul_f32 v[60:61], v[60:61], v[8:9] op_sel_hi:[1,0]
	v_pk_mul_f32 v[58:59], v[58:59], v[8:9] op_sel_hi:[1,0]
	v_pk_mul_f32 v[56:57], v[56:57], v[8:9] op_sel_hi:[1,0]
	v_pk_mul_f32 v[54:55], v[54:55], v[8:9] op_sel_hi:[1,0]
	v_pk_mul_f32 v[52:53], v[52:53], v[8:9] op_sel_hi:[1,0]
	v_pk_mul_f32 v[50:51], v[50:51], v[8:9] op_sel_hi:[1,0]
	v_sub_f32_e32 v35, v35, v7
	v_sub_f32_e32 v34, v34, v7
	v_sub_f32_e32 v45, v45, v7
	v_sub_f32_e32 v44, v44, v7
	v_sub_f32_e32 v43, v43, v7
	v_sub_f32_e32 v42, v42, v7
	v_sub_f32_e32 v41, v41, v7
	v_sub_f32_e32 v40, v40, v7
	v_sub_f32_e32 v39, v39, v7
	v_sub_f32_e32 v38, v38, v7
	v_sub_f32_e32 v49, v49, v7
	v_sub_f32_e32 v48, v48, v7
	v_sub_f32_e32 v47, v47, v7
	v_sub_f32_e32 v46, v46, v7
	v_pk_mul_f32 v[84:85], v[84:85], v[8:9] op_sel_hi:[1,0]
	v_pk_mul_f32 v[82:83], v[82:83], v[8:9] op_sel_hi:[1,0]

.LBB0_821:
	s_and_b64 vcc, exec, s[54:55]
	s_cbranch_vccnz .LBB0_823
	ds_read_b128 v[172:175], v150
	ds_read_b128 v[176:179], v150 offset:6144
	ds_read_b128 v[180:183], v150 offset:1024
	ds_read_b128 v[184:187], v150 offset:2048
	ds_read_b128 v[188:191], v150 offset:3072
	ds_read_b128 v[212:215], v150 offset:4096
	ds_read_b128 v[216:219], v150 offset:5120
	ds_read_b128 v[220:223], v150 offset:7168
	v_xor_b32_e32 v38, 0x80000000, v119
	v_mov_b32_e32 v39, v38
	v_mov_b32_e32 v40, v38
	v_mov_b32_e32 v41, v38
	s_nop 0
	s_waitcnt lgkmcnt(7)
	s_nop 0
	v_mfma_f32_16x16x32_bf16 v[34:37], v[172:175], v[10:13], v[38:41]
	ds_read_b128 v[172:175], v150 offset:8192
	s_waitcnt lgkmcnt(7)
	v_mfma_f32_16x16x32_bf16 v[38:41], v[176:179], v[10:13], v[38:41]
	ds_read_b128 v[176:179], v150 offset:9216
	s_waitcnt lgkmcnt(7)
	v_mfma_f32_16x16x32_bf16 v[34:37], v[180:183], v[14:17], v[34:37]
	ds_read_b128 v[180:183], v150 offset:10240
	s_waitcnt lgkmcnt(7)
	v_mfma_f32_16x16x32_bf16 v[34:37], v[184:187], v[18:21], v[34:37]
	ds_read_b128 v[184:187], v150 offset:11264
	s_waitcnt lgkmcnt(7)
	v_mfma_f32_16x16x32_bf16 v[34:37], v[188:191], v[22:25], v[34:37]
	s_waitcnt lgkmcnt(6)
	v_mfma_f32_16x16x32_bf16 v[34:37], v[212:215], v[26:29], v[34:37]
	s_waitcnt lgkmcnt(5)
	v_mfma_f32_16x16x32_bf16 v[34:37], v[216:219], v[30:33], v[34:37]
	s_waitcnt lgkmcnt(4)
	v_mfma_f32_16x16x32_bf16 v[38:41], v[220:223], v[14:17], v[38:41]
	s_waitcnt lgkmcnt(3)
	v_mfma_f32_16x16x32_bf16 v[38:41], v[172:175], v[18:21], v[38:41]
	s_waitcnt lgkmcnt(2)
	v_mfma_f32_16x16x32_bf16 v[38:41], v[176:179], v[22:25], v[38:41]
	s_waitcnt lgkmcnt(1)
	v_mfma_f32_16x16x32_bf16 v[38:41], v[180:183], v[26:29], v[38:41]
	s_waitcnt lgkmcnt(0)
	v_mfma_f32_16x16x32_bf16 v[38:41], v[184:187], v[30:33], v[38:41]
.LBB0_823:
	v_max_f32_e32 v7, v42, v43
	v_max_f32_e32 v8, v44, v45
	v_max_f32_e32 v121, v48, v48
	v_max_f32_e32 v9, v121, v49
	ds_read_b128 v[86:89], v152
	ds_read_b128 v[90:93], v153
	ds_read_b128 v[94:97], v154
	ds_read_b128 v[98:101], v155
	ds_read_b128 v[102:105], v156
	ds_read_b128 v[106:109], v157
	ds_read_b128 v[110:113], v158
	ds_read_b128 v[114:117], v159
	v_max3_f32 v9, v46, v47, v9
	v_max3_f32 v7, v7, v8, v9
	v_mov_b32_e32 v8, v7
	s_nop 1
	v_permlane16_swap_b32_e32 v7, v8
	v_max_f32_e32 v7, v7, v8
	v_mov_b32_e32 v8, v7
	s_nop 1
	v_permlane32_swap_b32_e32 v7, v8
	v_max_f32_e32 v7, v7, v8
	v_cmp_lt_f32_e32 vcc, s29, v7
	s_cbranch_vccz .LBB0_796
	v_max_f32_e32 v7, 0, v7
	v_exp_f32_e64 v8, -v7
	v_sub_f32_e32 v121, v35, v7
	v_sub_f32_e32 v160, v36, v7
	v_add_f32_e32 v119, v119, v7
	v_pk_mul_f32 v[80:81], v[80:81], v[8:9] op_sel_hi:[1,0]
	v_pk_mul_f32 v[78:79], v[78:79], v[8:9] op_sel_hi:[1,0]
	v_pk_mul_f32 v[76:77], v[76:77], v[8:9] op_sel_hi:[1,0]
	v_pk_mul_f32 v[74:75], v[74:75], v[8:9] op_sel_hi:[1,0]
	v_pk_mul_f32 v[72:73], v[72:73], v[8:9] op_sel_hi:[1,0]
	v_pk_mul_f32 v[70:71], v[70:71], v[8:9] op_sel_hi:[1,0]
	v_pk_mul_f32 v[68:69], v[68:69], v[8:9] op_sel_hi:[1,0]
	v_pk_mul_f32 v[66:67], v[66:67], v[8:9] op_sel_hi:[1,0]
	v_pk_mul_f32 v[64:65], v[64:65], v[8:9] op_sel_hi:[1,0]
	v_pk_mul_f32 v[62:63], v[62:63], v[8:9] op_sel_hi:[1,0]
	v_pk_mul_f32 v[60:61], v[60:61], v[8:9] op_sel_hi:[1,0]
	v_pk_mul_f32 v[58:59], v[58:59], v[8:9] op_sel_hi:[1,0]
	v_pk_mul_f32 v[56:57], v[56:57], v[8:9] op_sel_hi:[1,0]
	v_pk_mul_f32 v[54:55], v[54:55], v[8:9] op_sel_hi:[1,0]
	v_pk_mul_f32 v[52:53], v[52:53], v[8:9] op_sel_hi:[1,0]
	v_pk_mul_f32 v[50:51], v[50:51], v[8:9] op_sel_hi:[1,0]
	v_sub_f32_e32 v9, v34, v7
	v_sub_f32_e32 v42, v42, v7
	v_sub_f32_e32 v43, v43, v7
	v_sub_f32_e32 v44, v44, v7
	v_sub_f32_e32 v45, v45, v7
	v_sub_f32_e32 v161, v37, v7
	v_cndmask_b32_e64 v36, v36, v160, s[52:53]
	v_cndmask_b32_e64 v35, v35, v121, s[52:53]
	v_cndmask_b32_e64 v34, v34, v9, s[52:53]
	v_sub_f32_e32 v46, v46, v7
	v_sub_f32_e32 v47, v47, v7
	v_sub_f32_e32 v48, v48, v7
	v_sub_f32_e32 v49, v49, v7
	v_sub_f32_e32 v9, v38, v7
	v_sub_f32_e32 v121, v39, v7
	v_sub_f32_e32 v160, v40, v7
	v_sub_f32_e32 v7, v41, v7
	v_cndmask_b32_e64 v37, v37, v161, s[52:53]
	v_cndmask_b32_e64 v41, v41, v7, s[52:53]
	v_cndmask_b32_e64 v40, v40, v160, s[52:53]
	v_cndmask_b32_e64 v39, v39, v121, s[52:53]
	v_cndmask_b32_e64 v38, v38, v9, s[52:53]
	v_pk_mul_f32 v[84:85], v[84:85], v[8:9] op_sel_hi:[1,0]
	v_pk_mul_f32 v[82:83], v[82:83], v[8:9] op_sel_hi:[1,0]
	s_branch .LBB0_796

.LBB0_831:
	s_waitcnt vmcnt(1)
	s_lshl_b32 s90, s12, s19
	s_add_i32 s27, s22, 0x6000
	s_waitcnt lgkmcnt(0)
	s_barrier
	v_lshl_add_u64 v[8:9], v[140:141], 0, s[90:91]
	s_mov_b32 m0, s27
	v_xor_b32_e32 v66, 0x80000000, v142
	global_load_lds_dwordx4 v[8:9], off
	ds_read_b128 v[42:45], v150 offset:8192
	ds_read_b128 v[46:49], v150 offset:9216
	ds_read_b128 v[98:101], v150 offset:10240
	ds_read_b128 v[102:105], v150 offset:11264
	v_xor_b32_e32 v106, 0x80000000, v143
	v_mov_b32_e32 v67, v66
	v_mov_b32_e32 v68, v66
	v_mov_b32_e32 v69, v66
	v_mov_b32_e32 v107, v106
	v_mov_b32_e32 v108, v106
	v_mov_b32_e32 v109, v106
	s_waitcnt lgkmcnt(0)
	v_mfma_f32_16x16x32_bf16 v[70:73], v[42:45], v[10:13], v[66:69]
	v_max_f32_e32 v2, v34, v35
	v_mfma_f32_16x16x32_bf16 v[42:45], v[42:45], v[14:17], v[106:109]
	v_max_f32_e32 v7, v36, v37
	v_max_f32_e32 v9, v40, v40
	v_mfma_f32_16x16x32_bf16 v[70:73], v[46:49], v[18:21], v[70:73]
	v_max_f32_e32 v8, v9, v41
	v_max3_f32 v8, v38, v39, v8
	v_max3_f32 v2, v2, v7, v8
	v_mfma_f32_16x16x32_bf16 v[66:69], v[98:101], v[10:13], v[66:69]
	v_mov_b32_e32 v7, v2
	s_nop 1
	v_permlane16_swap_b32_e32 v2, v7
	v_mfma_f32_16x16x32_bf16 v[46:49], v[46:49], v[22:25], v[42:45]
	v_max_f32_e32 v2, v2, v7
	v_mfma_f32_16x16x32_bf16 v[42:45], v[98:101], v[14:17], v[106:109]
	v_mov_b32_e32 v7, v2
	s_nop 1
	v_permlane32_swap_b32_e32 v2, v7
	v_mfma_f32_16x16x32_bf16 v[66:69], v[102:105], v[18:21], v[66:69]
	v_max_f32_e32 v2, v2, v7
	v_mfma_f32_16x16x32_bf16 v[42:45], v[102:105], v[22:25], v[42:45]
	ds_read_b128 v[102:105], v150 offset:4096
	ds_read_b128 v[106:109], v150 offset:5120
	ds_read_b128 v[110:113], v150 offset:6144
	ds_read_b128 v[114:117], v150 offset:7168
	s_and_b64 vcc, exec, s[10:11]
	s_cbranch_vccnz .LBB0_834
	v_cmp_lt_f32_e32 vcc, s29, v2
	s_cbranch_vccz .LBB0_865
	v_max_f32_e32 v2, 0, v2

.LBB0_836:
	v_exp_f32_e32 v2, v34
	v_exp_f32_e32 v7, v35
	v_exp_f32_e32 v8, v36
	v_exp_f32_e32 v9, v37
	v_exp_f32_e32 v36, v38
	v_exp_f32_e32 v37, v39
	v_exp_f32_e32 v38, v40
	v_exp_f32_e32 v39, v41
	v_cvt_pk_bf16_f32 v34, v2, v7
	v_cvt_pk_bf16_f32 v35, v8, v9
	v_mov_b32_e32 v7, v6
	v_mov_b32_e32 v8, v6
	v_mov_b32_e32 v9, v6
	v_cvt_pk_bf16_f32 v36, v36, v37
	v_cvt_pk_bf16_f32 v37, v38, v39
	s_xor_b64 s[12:13], s[10:11], -1
	s_waitcnt lgkmcnt(0)
	v_mfma_f32_16x16x32_bf16 v[98:101], v[102:105], v[34:37], v[74:77]
	s_andn2_b64 vcc, exec, s[12:13]
	v_mfma_f32_16x16x32_bf16 v[74:77], v[114:117], v[34:37], v[82:85]
	v_mfma_f32_16x16x32_bf16 v[82:85], v[6:9], v[34:37], v[94:97]
	v_max_f32_e32 v2, v26, v27
	v_max_f32_e32 v7, v28, v29
	v_max_f32_e32 v9, v32, v32
	v_max_f32_e32 v8, v9, v33
	v_max3_f32 v8, v30, v31, v8
	v_max3_f32 v2, v2, v7, v8
	v_mov_b32_e32 v7, v2
	s_nop 1
	v_permlane16_swap_b32_e32 v2, v7
	v_max_f32_e32 v2, v2, v7
	v_mov_b32_e32 v7, v2
	v_mfma_f32_16x16x32_bf16 v[86:89], v[106:109], v[34:37], v[86:89]
	s_nop 0
	v_permlane32_swap_b32_e32 v2, v7
	v_mfma_f32_16x16x32_bf16 v[78:81], v[110:113], v[34:37], v[78:81]
	v_max_f32_e32 v2, v2, v7
	v_cndmask_b32_e64 v7, 0, 1, s[12:13]
	v_cmp_ne_u32_e64 s[52:53], 1, v7
	s_mov_b64 s[12:13], -1
	s_cbranch_vccnz .LBB0_839
	v_cmp_lt_f32_e32 vcc, s29, v2
	s_cbranch_vccz .LBB0_866
	v_max_f32_e32 v2, 0, v2

.LBB0_843:
	ds_read_b128 v[26:29], v150 offset:16384
	ds_read_b128 v[30:33], v150 offset:17408
	ds_read_b128 v[90:93], v150 offset:18432
	ds_read_b128 v[94:97], v150 offset:19456
	v_xor_b32_e32 v38, 0x80000000, v142
	v_xor_b32_e32 v106, 0x80000000, v143
	v_max_f32_e32 v2, v70, v71
	v_mov_b32_e32 v39, v38
	v_mov_b32_e32 v40, v38
	v_mov_b32_e32 v41, v38
	v_mov_b32_e32 v107, v106
	v_mov_b32_e32 v108, v106
	v_mov_b32_e32 v109, v106
	v_max_f32_e32 v7, v72, v73
	v_max_f32_e32 v9, v68, v68
	s_waitcnt lgkmcnt(0)
	v_mfma_f32_16x16x32_bf16 v[34:37], v[26:29], v[10:13], v[38:41]
	v_max_f32_e32 v8, v9, v69
	v_max3_f32 v8, v66, v67, v8
	v_max3_f32 v2, v2, v7, v8
	v_mfma_f32_16x16x32_bf16 v[26:29], v[26:29], v[14:17], v[106:109]
	v_mov_b32_e32 v7, v2
	s_nop 1
	v_permlane16_swap_b32_e32 v2, v7
	v_mfma_f32_16x16x32_bf16 v[34:37], v[30:33], v[18:21], v[34:37]
	v_max_f32_e32 v2, v2, v7
	v_mfma_f32_16x16x32_bf16 v[38:41], v[90:93], v[10:13], v[38:41]
	v_mov_b32_e32 v7, v2
	s_nop 1
	v_permlane32_swap_b32_e32 v2, v7
	v_mfma_f32_16x16x32_bf16 v[26:29], v[30:33], v[22:25], v[26:29]
	v_max_f32_e32 v2, v2, v7
	v_mfma_f32_16x16x32_bf16 v[30:33], v[90:93], v[14:17], v[106:109]
	s_nop 2
	ds_read_b128 v[106:109], v150 offset:12288
	ds_read_b128 v[110:113], v150 offset:13312
	ds_read_b128 v[114:117], v150 offset:14336
	ds_read_b128 v[118:121], v150 offset:15360
	v_cmp_lt_f32_e32 vcc, s29, v2
	v_mfma_f32_16x16x32_bf16 v[38:41], v[94:97], v[18:21], v[38:41]
	v_mfma_f32_16x16x32_bf16 v[30:33], v[94:97], v[22:25], v[30:33]
	s_cbranch_vccz .LBB0_845
	v_max_f32_e32 v7, 0, v2
	v_exp_f32_e64 v2, -v7
	v_add_f32_e32 v142, v142, v7
	v_sub_f32_e32 v70, v70, v7
	v_sub_f32_e32 v71, v71, v7
	v_pk_mul_f32 v[84:85], v[84:85], v[2:3] op_sel_hi:[1,0]
	v_pk_mul_f32 v[82:83], v[82:83], v[2:3] op_sel_hi:[1,0]
	v_pk_mul_f32 v[100:101], v[100:101], v[2:3] op_sel_hi:[1,0]
	v_pk_mul_f32 v[98:99], v[98:99], v[2:3] op_sel_hi:[1,0]
	v_pk_mul_f32 v[88:89], v[88:89], v[2:3] op_sel_hi:[1,0]
	v_pk_mul_f32 v[86:87], v[86:87], v[2:3] op_sel_hi:[1,0]
	v_pk_mul_f32 v[80:81], v[80:81], v[2:3] op_sel_hi:[1,0]
	v_pk_mul_f32 v[78:79], v[78:79], v[2:3] op_sel_hi:[1,0]
	v_pk_mul_f32 v[76:77], v[76:77], v[2:3] op_sel_hi:[1,0]
	v_pk_mul_f32 v[74:75], v[74:75], v[2:3] op_sel_hi:[1,0]
	v_sub_f32_e32 v72, v72, v7
	v_sub_f32_e32 v73, v73, v7
	v_sub_f32_e32 v37, v37, v7
	v_sub_f32_e32 v36, v36, v7
	v_sub_f32_e32 v35, v35, v7
	v_sub_f32_e32 v34, v34, v7
	v_sub_f32_e32 v66, v66, v7
	v_sub_f32_e32 v67, v67, v7
	v_sub_f32_e32 v68, v68, v7
	v_sub_f32_e32 v69, v69, v7
	v_sub_f32_e32 v41, v41, v7
	v_sub_f32_e32 v40, v40, v7
	v_sub_f32_e32 v39, v39, v7
	v_sub_f32_e32 v38, v38, v7
.LBB0_845:
	v_exp_f32_e32 v2, v70
	v_exp_f32_e32 v7, v71
	v_exp_f32_e32 v8, v72
	v_exp_f32_e32 v9, v73
	v_exp_f32_e32 v70, v66
	v_exp_f32_e32 v71, v67
	v_exp_f32_e32 v72, v68
	v_exp_f32_e32 v69, v69
	v_cvt_pk_bf16_f32 v66, v2, v7
	v_cvt_pk_bf16_f32 v67, v8, v9
	v_mov_b32_e32 v7, v6
	v_mov_b32_e32 v8, v6
	v_mov_b32_e32 v9, v6
	v_cvt_pk_bf16_f32 v68, v70, v71
	v_cvt_pk_bf16_f32 v69, v72, v69
	s_waitcnt lgkmcnt(0)
	s_nop 1
	v_mfma_f32_16x16x32_bf16 v[94:97], v[106:109], v[66:69], v[98:101]
	v_mfma_f32_16x16x32_bf16 v[90:93], v[110:113], v[66:69], v[86:89]
	v_mfma_f32_16x16x32_bf16 v[86:89], v[114:117], v[66:69], v[78:81]
	v_mfma_f32_16x16x32_bf16 v[78:81], v[118:121], v[66:69], v[74:77]
	v_mfma_f32_16x16x32_bf16 v[82:85], v[6:9], v[66:69], v[82:85]
	v_max_f32_e32 v2, v46, v47
	v_max_f32_e32 v66, v48, v49
	v_max_f32_e32 v68, v44, v44
	v_max_f32_e32 v67, v68, v45
	v_max3_f32 v67, v42, v43, v67
	v_max3_f32 v2, v2, v66, v67
	v_mov_b32_e32 v66, v2
	s_nop 1
	v_permlane16_swap_b32_e32 v2, v66
	v_max_f32_e32 v2, v2, v66
	v_mov_b32_e32 v66, v2
	s_nop 1
	v_permlane32_swap_b32_e32 v2, v66
	v_max_f32_e32 v2, v2, v66
	v_cmp_lt_f32_e32 vcc, s29, v2
	s_cbranch_vccz .LBB0_847
	v_max_f32_e32 v66, 0, v2
	v_exp_f32_e64 v2, -v66
	v_add_f32_e32 v143, v143, v66
	v_sub_f32_e32 v46, v46, v66
	v_sub_f32_e32 v47, v47, v66
	v_pk_mul_f32 v[104:105], v[104:105], v[2:3] op_sel_hi:[1,0]
	v_pk_mul_f32 v[102:103], v[102:103], v[2:3] op_sel_hi:[1,0]
	v_pk_mul_f32 v[64:65], v[64:65], v[2:3] op_sel_hi:[1,0]
	v_pk_mul_f32 v[62:63], v[62:63], v[2:3] op_sel_hi:[1,0]
	v_pk_mul_f32 v[60:61], v[60:61], v[2:3] op_sel_hi:[1,0]
	v_pk_mul_f32 v[58:59], v[58:59], v[2:3] op_sel_hi:[1,0]
	v_pk_mul_f32 v[56:57], v[56:57], v[2:3] op_sel_hi:[1,0]
	v_pk_mul_f32 v[54:55], v[54:55], v[2:3] op_sel_hi:[1,0]
	v_pk_mul_f32 v[52:53], v[52:53], v[2:3] op_sel_hi:[1,0]
	v_pk_mul_f32 v[50:51], v[50:51], v[2:3] op_sel_hi:[1,0]
	v_sub_f32_e32 v48, v48, v66
	v_sub_f32_e32 v49, v49, v66
	v_sub_f32_e32 v29, v29, v66
	v_sub_f32_e32 v28, v28, v66
	v_sub_f32_e32 v27, v27, v66
	v_sub_f32_e32 v26, v26, v66
	v_sub_f32_e32 v42, v42, v66
	v_sub_f32_e32 v43, v43, v66
	v_sub_f32_e32 v44, v44, v66
	v_sub_f32_e32 v45, v45, v66
	v_sub_f32_e32 v33, v33, v66
	v_sub_f32_e32 v32, v32, v66
	v_sub_f32_e32 v31, v31, v66
	v_sub_f32_e32 v30, v30, v66

.LBB0_853:
	ds_read_b128 v[42:45], v150 offset:24576
	ds_read_b128 v[46:49], v150 offset:25600
	ds_read_b128 v[98:101], v150 offset:26624
	ds_read_b128 v[102:105], v150 offset:27648
	v_xor_b32_e32 v54, 0x80000000, v142
	v_xor_b32_e32 v106, 0x80000000, v143
	v_max_f32_e32 v2, v34, v35
	v_mov_b32_e32 v55, v54
	v_mov_b32_e32 v56, v54
	v_mov_b32_e32 v57, v54
	v_mov_b32_e32 v107, v106
	v_mov_b32_e32 v108, v106
	v_mov_b32_e32 v109, v106
	v_max_f32_e32 v7, v36, v37
	v_max_f32_e32 v9, v40, v40
	s_waitcnt lgkmcnt(0)
	v_mfma_f32_16x16x32_bf16 v[50:53], v[42:45], v[10:13], v[54:57]
	v_max_f32_e32 v8, v9, v41
	v_max3_f32 v8, v38, v39, v8
	v_max3_f32 v2, v2, v7, v8
	v_mfma_f32_16x16x32_bf16 v[42:45], v[42:45], v[14:17], v[106:109]
	v_mov_b32_e32 v7, v2
	s_nop 1
	v_permlane16_swap_b32_e32 v2, v7
	v_mfma_f32_16x16x32_bf16 v[50:53], v[46:49], v[18:21], v[50:53]
	ds_read_b128 v[110:113], v150 offset:20480
	ds_read_b128 v[114:117], v150 offset:21504
	ds_read_b128 v[122:125], v150 offset:22528
	ds_read_b128 v[126:129], v150 offset:23552
	v_mfma_f32_16x16x32_bf16 v[54:57], v[98:101], v[10:13], v[54:57]
	v_max_f32_e32 v2, v2, v7
	v_mov_b32_e32 v7, v2
	s_nop 1
	v_permlane32_swap_b32_e32 v2, v7
	v_mfma_f32_16x16x32_bf16 v[46:49], v[46:49], v[22:25], v[42:45]
	v_max_f32_e32 v2, v2, v7
	v_mfma_f32_16x16x32_bf16 v[42:45], v[98:101], v[14:17], v[106:109]
	v_cmp_lt_f32_e32 vcc, s29, v2
	v_mfma_f32_16x16x32_bf16 v[54:57], v[102:105], v[18:21], v[54:57]
	v_mfma_f32_16x16x32_bf16 v[42:45], v[102:105], v[22:25], v[42:45]
	s_cbranch_vccz .LBB0_855
	v_max_f32_e32 v7, 0, v2
	v_exp_f32_e64 v2, -v7
	v_add_f32_e32 v142, v142, v7
	v_sub_f32_e32 v37, v37, v7
	v_sub_f32_e32 v36, v36, v7
	v_pk_mul_f32 v[84:85], v[84:85], v[2:3] op_sel_hi:[1,0]
	v_pk_mul_f32 v[82:83], v[82:83], v[2:3] op_sel_hi:[1,0]
	v_pk_mul_f32 v[96:97], v[96:97], v[2:3] op_sel_hi:[1,0]
	v_pk_mul_f32 v[94:95], v[94:95], v[2:3] op_sel_hi:[1,0]
	v_pk_mul_f32 v[92:93], v[92:93], v[2:3] op_sel_hi:[1,0]
	v_pk_mul_f32 v[90:91], v[90:91], v[2:3] op_sel_hi:[1,0]
	v_pk_mul_f32 v[88:89], v[88:89], v[2:3] op_sel_hi:[1,0]
	v_pk_mul_f32 v[86:87], v[86:87], v[2:3] op_sel_hi:[1,0]
	v_pk_mul_f32 v[80:81], v[80:81], v[2:3] op_sel_hi:[1,0]
	v_pk_mul_f32 v[78:79], v[78:79], v[2:3] op_sel_hi:[1,0]
	v_sub_f32_e32 v35, v35, v7
	v_sub_f32_e32 v34, v34, v7
	v_sub_f32_e32 v53, v53, v7
	v_sub_f32_e32 v52, v52, v7
	v_sub_f32_e32 v51, v51, v7
	v_sub_f32_e32 v50, v50, v7
	v_sub_f32_e32 v41, v41, v7
	v_sub_f32_e32 v40, v40, v7
	v_sub_f32_e32 v39, v39, v7
	v_sub_f32_e32 v38, v38, v7
	v_sub_f32_e32 v57, v57, v7
	v_sub_f32_e32 v56, v56, v7
	v_sub_f32_e32 v55, v55, v7
	v_sub_f32_e32 v54, v54, v7
.LBB0_855:
	v_exp_f32_e32 v2, v34
	v_exp_f32_e32 v7, v35
	v_exp_f32_e32 v8, v36
	v_exp_f32_e32 v9, v37
	v_exp_f32_e32 v98, v38
	v_exp_f32_e32 v99, v39
	v_exp_f32_e32 v100, v40
	v_exp_f32_e32 v101, v41
	v_cvt_pk_bf16_f32 v106, v2, v7
	v_cvt_pk_bf16_f32 v107, v8, v9
	v_cvt_pk_bf16_f32 v108, v98, v99
	v_cvt_pk_bf16_f32 v109, v100, v101
	v_mov_b32_e32 v7, v6
	s_waitcnt lgkmcnt(0)
	v_mfma_f32_16x16x32_bf16 v[98:101], v[114:117], v[106:109], v[90:93]
	v_mov_b32_e32 v8, v6
	v_mov_b32_e32 v9, v6
	v_mfma_f32_16x16x32_bf16 v[90:93], v[126:129], v[106:109], v[78:81]
	s_nop 2
	v_max_f32_e32 v2, v26, v27
	v_max_f32_e32 v78, v28, v29
	v_max_f32_e32 v80, v32, v32
	v_max_f32_e32 v79, v80, v33
	v_max3_f32 v79, v30, v31, v79
	v_max3_f32 v2, v2, v78, v79
	v_mov_b32_e32 v78, v2
	s_nop 1
	v_permlane16_swap_b32_e32 v2, v78
	v_max_f32_e32 v2, v2, v78
	v_mov_b32_e32 v78, v2
	v_mfma_f32_16x16x32_bf16 v[102:105], v[110:113], v[106:109], v[94:97]
	s_nop 0
	v_permlane32_swap_b32_e32 v2, v78
	v_mfma_f32_16x16x32_bf16 v[94:97], v[122:125], v[106:109], v[86:89]
	v_max_f32_e32 v2, v2, v78
	v_cmp_lt_f32_e32 vcc, s29, v2
	v_mfma_f32_16x16x32_bf16 v[106:109], v[6:9], v[106:109], v[82:85]
	s_cbranch_vccz .LBB0_857
	v_max_f32_e32 v78, 0, v2
	v_exp_f32_e64 v2, -v78
	v_add_f32_e32 v143, v143, v78
	v_sub_f32_e32 v29, v29, v78
	v_sub_f32_e32 v28, v28, v78
	v_pk_mul_f32 v[60:61], v[60:61], v[2:3] op_sel_hi:[1,0]
	v_pk_mul_f32 v[58:59], v[58:59], v[2:3] op_sel_hi:[1,0]
	v_pk_mul_f32 v[76:77], v[76:77], v[2:3] op_sel_hi:[1,0]
	v_pk_mul_f32 v[74:75], v[74:75], v[2:3] op_sel_hi:[1,0]
	v_pk_mul_f32 v[72:73], v[72:73], v[2:3] op_sel_hi:[1,0]
	v_pk_mul_f32 v[70:71], v[70:71], v[2:3] op_sel_hi:[1,0]
	v_pk_mul_f32 v[68:69], v[68:69], v[2:3] op_sel_hi:[1,0]
	v_pk_mul_f32 v[66:67], v[66:67], v[2:3] op_sel_hi:[1,0]
	v_pk_mul_f32 v[64:65], v[64:65], v[2:3] op_sel_hi:[1,0]
	v_pk_mul_f32 v[62:63], v[62:63], v[2:3] op_sel_hi:[1,0]
	v_sub_f32_e32 v27, v27, v78
	v_sub_f32_e32 v26, v26, v78
	v_sub_f32_e32 v49, v49, v78
	v_sub_f32_e32 v48, v48, v78
	v_sub_f32_e32 v47, v47, v78
	v_sub_f32_e32 v46, v46, v78
	v_sub_f32_e32 v33, v33, v78
	v_sub_f32_e32 v32, v32, v78
	v_sub_f32_e32 v31, v31, v78
	v_sub_f32_e32 v30, v30, v78
	v_sub_f32_e32 v45, v45, v78
	v_sub_f32_e32 v44, v44, v78
	v_sub_f32_e32 v43, v43, v78
	v_sub_f32_e32 v42, v42, v78

.LBB0_861:
	v_max_f32_e32 v2, v50, v51
	v_max_f32_e32 v7, v52, v53
	v_max_f32_e32 v9, v56, v56
	v_max_f32_e32 v8, v9, v57
	v_max3_f32 v8, v54, v55, v8
	v_max3_f32 v2, v2, v7, v8
	v_mov_b32_e32 v7, v2
	s_nop 1
	v_permlane16_swap_b32_e32 v2, v7
	ds_read_b128 v[58:61], v150 offset:28672
	ds_read_b128 v[122:125], v150 offset:29696
	ds_read_b128 v[126:129], v150 offset:30720
	ds_read_b128 v[130:133], v150 offset:31744
	v_max_f32_e32 v2, v2, v7
	v_mov_b32_e32 v7, v2
	s_nop 1
	v_permlane32_swap_b32_e32 v2, v7
	v_max_f32_e32 v2, v2, v7
	v_cmp_lt_f32_e32 vcc, s29, v2
	s_cbranch_vccz .LBB0_863
	v_max_f32_e32 v7, 0, v2
	v_exp_f32_e64 v2, -v7
	v_sub_f32_e32 v8, v35, v7
	v_sub_f32_e32 v9, v36, v7
	v_add_f32_e32 v142, v142, v7
	v_pk_mul_f32 v[108:109], v[108:109], v[2:3] op_sel_hi:[1,0]
	v_pk_mul_f32 v[106:107], v[106:107], v[2:3] op_sel_hi:[1,0]
	v_pk_mul_f32 v[104:105], v[104:105], v[2:3] op_sel_hi:[1,0]
	v_pk_mul_f32 v[102:103], v[102:103], v[2:3] op_sel_hi:[1,0]
	v_pk_mul_f32 v[100:101], v[100:101], v[2:3] op_sel_hi:[1,0]
	v_pk_mul_f32 v[98:99], v[98:99], v[2:3] op_sel_hi:[1,0]
	v_pk_mul_f32 v[96:97], v[96:97], v[2:3] op_sel_hi:[1,0]
	v_pk_mul_f32 v[94:95], v[94:95], v[2:3] op_sel_hi:[1,0]
	v_pk_mul_f32 v[92:93], v[92:93], v[2:3] op_sel_hi:[1,0]
	v_pk_mul_f32 v[90:91], v[90:91], v[2:3] op_sel_hi:[1,0]
	v_sub_f32_e32 v2, v34, v7
	v_sub_f32_e32 v50, v50, v7
	v_sub_f32_e32 v51, v51, v7
	v_sub_f32_e32 v52, v52, v7
	v_sub_f32_e32 v53, v53, v7
	v_sub_f32_e32 v62, v37, v7
	v_cndmask_b32_e64 v36, v36, v9, s[10:11]
	v_cndmask_b32_e64 v35, v35, v8, s[10:11]
	v_cndmask_b32_e64 v34, v34, v2, s[10:11]
	v_sub_f32_e32 v54, v54, v7
	v_sub_f32_e32 v55, v55, v7
	v_sub_f32_e32 v56, v56, v7
	v_sub_f32_e32 v57, v57, v7
	v_sub_f32_e32 v2, v38, v7
	v_sub_f32_e32 v8, v39, v7
	v_sub_f32_e32 v9, v40, v7
	v_sub_f32_e32 v7, v41, v7
	v_cndmask_b32_e64 v37, v37, v62, s[10:11]
	v_cndmask_b32_e64 v41, v41, v7, s[10:11]
	v_cndmask_b32_e64 v40, v40, v9, s[10:11]
	v_cndmask_b32_e64 v39, v39, v8, s[10:11]
	v_cndmask_b32_e64 v38, v38, v2, s[10:11]
.LBB0_863:
	v_exp_f32_e32 v2, v50
	v_exp_f32_e32 v7, v51
	v_exp_f32_e32 v8, v52
	v_exp_f32_e32 v9, v53
	v_exp_f32_e32 v52, v54
	v_exp_f32_e32 v53, v55
	v_exp_f32_e32 v54, v56
	v_exp_f32_e32 v55, v57
	v_cvt_pk_bf16_f32 v50, v2, v7
	v_cvt_pk_bf16_f32 v51, v8, v9
	v_mov_b32_e32 v7, v6
	v_mov_b32_e32 v8, v6
	v_mov_b32_e32 v9, v6
	v_cvt_pk_bf16_f32 v52, v52, v53
	v_cvt_pk_bf16_f32 v53, v54, v55
	s_waitcnt lgkmcnt(0)
	s_nop 1
	v_mfma_f32_16x16x32_bf16 v[74:77], v[58:61], v[50:53], v[102:105]
	v_mfma_f32_16x16x32_bf16 v[86:89], v[122:125], v[50:53], v[98:101]
	v_mfma_f32_16x16x32_bf16 v[78:81], v[126:129], v[50:53], v[94:97]
	v_mfma_f32_16x16x32_bf16 v[82:85], v[130:133], v[50:53], v[90:93]
	v_mfma_f32_16x16x32_bf16 v[94:97], v[6:9], v[50:53], v[106:109]
	v_max_f32_e32 v2, v46, v47
	v_max_f32_e32 v50, v48, v49
	v_max_f32_e32 v52, v44, v44
	v_max_f32_e32 v51, v52, v45
	v_max3_f32 v51, v42, v43, v51
	v_max3_f32 v2, v2, v50, v51
	v_mov_b32_e32 v50, v2
	s_nop 1
	v_permlane16_swap_b32_e32 v2, v50
	v_max_f32_e32 v2, v2, v50
	v_mov_b32_e32 v50, v2
	s_nop 1
	v_permlane32_swap_b32_e32 v2, v50
	v_max_f32_e32 v2, v2, v50
	v_cmp_lt_f32_e32 vcc, s29, v2
	s_cbranch_vccz .LBB0_830
	v_max_f32_e32 v50, 0, v2
	v_exp_f32_e64 v2, -v50
	v_sub_f32_e32 v51, v27, v50
	v_sub_f32_e32 v52, v28, v50
	v_add_f32_e32 v143, v143, v50
	v_pk_mul_f32 v[68:69], v[68:69], v[2:3] op_sel_hi:[1,0]
	v_pk_mul_f32 v[66:67], v[66:67], v[2:3] op_sel_hi:[1,0]
	v_pk_mul_f32 v[120:121], v[120:121], v[2:3] op_sel_hi:[1,0]
	v_pk_mul_f32 v[118:119], v[118:119], v[2:3] op_sel_hi:[1,0]
	v_pk_mul_f32 v[116:117], v[116:117], v[2:3] op_sel_hi:[1,0]
	v_pk_mul_f32 v[114:115], v[114:115], v[2:3] op_sel_hi:[1,0]
	v_pk_mul_f32 v[112:113], v[112:113], v[2:3] op_sel_hi:[1,0]
	v_pk_mul_f32 v[110:111], v[110:111], v[2:3] op_sel_hi:[1,0]
	v_pk_mul_f32 v[72:73], v[72:73], v[2:3] op_sel_hi:[1,0]
	v_pk_mul_f32 v[70:71], v[70:71], v[2:3] op_sel_hi:[1,0]
	v_sub_f32_e32 v2, v26, v50
	v_sub_f32_e32 v46, v46, v50
	v_sub_f32_e32 v47, v47, v50
	v_sub_f32_e32 v48, v48, v50
	v_sub_f32_e32 v49, v49, v50
	v_sub_f32_e32 v53, v29, v50
	v_cndmask_b32_e64 v28, v28, v52, s[10:11]
	v_cndmask_b32_e64 v27, v27, v51, s[10:11]
	v_cndmask_b32_e64 v26, v26, v2, s[10:11]
	v_sub_f32_e32 v42, v42, v50
	v_sub_f32_e32 v43, v43, v50
	v_sub_f32_e32 v44, v44, v50
	v_sub_f32_e32 v45, v45, v50
	v_sub_f32_e32 v2, v30, v50
	v_sub_f32_e32 v51, v31, v50
	v_sub_f32_e32 v52, v32, v50
	v_sub_f32_e32 v50, v33, v50
	v_cndmask_b32_e64 v29, v29, v53, s[10:11]
	v_cndmask_b32_e64 v33, v33, v50, s[10:11]
	v_cndmask_b32_e64 v32, v32, v52, s[10:11]
	v_cndmask_b32_e64 v31, v31, v51, s[10:11]
	v_cndmask_b32_e64 v30, v30, v2, s[10:11]
	s_branch .LBB0_830

.LBB0_895:
	s_lshl_b32 s14, s11, 1
	s_mul_i32 s15, s10, s11
	s_and_b64 s[12:13], s[8:9], exec
	s_cselect_b32 s13, 0, 0
	s_cselect_b32 s12, s14, s15
	s_waitcnt vmcnt(3)
	v_lshl_add_u64 v[4:5], v[120:121], 0, s[12:13]
	s_mul_i32 s15, s16, s11
	s_and_b64 s[12:13], s[48:49], exec
	s_mov_b32 m0, s64
	s_waitcnt lgkmcnt(0)
	s_barrier
	s_cselect_b32 s13, 0, 0
	s_cselect_b32 s12, s14, s15
	global_load_lds_dwordx4 v[4:5], off
	v_lshl_add_u64 v[4:5], v[122:123], 0, s[12:13]
	s_mul_i32 s11, s20, s11
	s_and_b64 s[12:13], s[60:61], exec
	s_mov_b32 m0, s65
	s_cselect_b32 s13, 0, 0
	s_cselect_b32 s12, s14, s11
	global_load_lds_dwordx4 v[4:5], off
	v_lshl_add_u64 v[4:5], v[124:125], 0, s[12:13]
	s_mov_b32 m0, s84
	v_xor_b32_e32 v86, 0x80000000, v135
	global_load_lds_dwordx4 v[4:5], off
	ds_read_b128 v[196:199], v150 offset:24576
	ds_read_b128 v[208:211], v150 offset:25600
	ds_read_b128 v[212:215], v150 offset:26624
	ds_read_b128 v[216:219], v150 offset:27648
	ds_read_b128 v[220:223], v150 offset:28672
	ds_read_b128 v[224:227], v150 offset:29696
	ds_read_b128 v[228:231], v150 offset:30720
	ds_read_b128 v[240:243], v150 offset:31744
	v_mov_b32_e32 v87, v86
	v_mov_b32_e32 v88, v86
	v_mov_b32_e32 v89, v86
	s_waitcnt lgkmcnt(7)
	s_nop 0
	v_mfma_f32_16x16x32_bf16 v[42:45], v[196:199], v[10:13], v[86:89]
	ds_read_b128 v[196:199], v150 offset:32768
	v_max_f32_e32 v2, v34, v35
	s_waitcnt lgkmcnt(7)
	v_mfma_f32_16x16x32_bf16 v[42:45], v[208:211], v[14:17], v[42:45]
	ds_read_b128 v[208:211], v150 offset:33792
	v_max_f32_e32 v4, v36, v37
	s_waitcnt lgkmcnt(7)
	v_mfma_f32_16x16x32_bf16 v[42:45], v[212:215], v[18:21], v[42:45]
	ds_read_b128 v[212:215], v150 offset:34816
	v_max_f32_e32 v7, v40, v40
	s_waitcnt lgkmcnt(7)
	v_mfma_f32_16x16x32_bf16 v[42:45], v[216:219], v[22:25], v[42:45]
	ds_read_b128 v[216:219], v150 offset:35840
	v_max_f32_e32 v5, v7, v41
	v_max3_f32 v5, v38, v39, v5
	s_waitcnt lgkmcnt(7)
	v_mfma_f32_16x16x32_bf16 v[42:45], v[220:223], v[26:29], v[42:45]
	v_max3_f32 v2, v2, v4, v5
	v_mov_b32_e32 v4, v2
	s_waitcnt lgkmcnt(6)
	v_mfma_f32_16x16x32_bf16 v[42:45], v[224:227], v[30:33], v[42:45]
	v_permlane16_swap_b32_e32 v2, v4
	s_waitcnt lgkmcnt(5)
	v_mfma_f32_16x16x32_bf16 v[86:89], v[228:231], v[10:13], v[86:89]
	s_waitcnt lgkmcnt(4)
	v_mfma_f32_16x16x32_bf16 v[46:49], v[240:243], v[14:17], v[86:89]
	v_max_f32_e32 v2, v2, v4
	s_nop 1
	v_mov_b32_e32 v4, v2
	s_waitcnt lgkmcnt(3)
	v_mfma_f32_16x16x32_bf16 v[46:49], v[196:199], v[18:21], v[46:49]
	v_permlane32_swap_b32_e32 v2, v4
	s_waitcnt lgkmcnt(2)
	v_mfma_f32_16x16x32_bf16 v[46:49], v[208:211], v[22:25], v[46:49]
	s_waitcnt lgkmcnt(1)
	v_mfma_f32_16x16x32_bf16 v[46:49], v[212:215], v[26:29], v[46:49]
	v_max_f32_e32 v2, v2, v4
	s_and_b64 vcc, exec, s[24:25]
	s_waitcnt lgkmcnt(0)
	v_mfma_f32_16x16x32_bf16 v[46:49], v[216:219], v[30:33], v[46:49]
	ds_read_b128 v[86:89], v150 offset:12288
	ds_read_b128 v[90:93], v150 offset:13312
	ds_read_b128 v[94:97], v150 offset:14336
	ds_read_b128 v[98:101], v150 offset:15360
	ds_read_b128 v[102:105], v150 offset:16384
	ds_read_b128 v[106:109], v150 offset:17408
	ds_read_b128 v[110:113], v150 offset:18432
	ds_read_b128 v[114:117], v150 offset:19456
	s_cbranch_vccnz .LBB0_898
	v_cmp_lt_f32_e32 vcc, s29, v2
	s_cbranch_vccz .LBB0_918
	v_max_f32_e32 v2, 0, v2

.LBB0_902:
	v_xor_b32_e32 v188, 0x80000000, v135
	ds_read_b128 v[34:37], v150 offset:49152
	ds_read_b128 v[38:41], v150 offset:50176
	ds_read_b128 v[86:89], v150 offset:51200
	ds_read_b128 v[90:93], v150 offset:52224
	ds_read_b128 v[94:97], v150 offset:53248
	ds_read_b128 v[98:101], v150 offset:54272
	ds_read_b128 v[102:105], v150 offset:55296
	ds_read_b128 v[106:109], v150 offset:56320
	ds_read_b128 v[110:113], v150 offset:57344
	ds_read_b128 v[114:117], v150 offset:58368
	ds_read_b128 v[180:183], v150 offset:59392
	ds_read_b128 v[184:187], v150 offset:60416
	v_mov_b32_e32 v189, v188
	v_mov_b32_e32 v190, v188
	v_mov_b32_e32 v191, v188
	s_waitcnt lgkmcnt(0)
	s_nop 1
	v_mfma_f32_16x16x32_bf16 v[34:37], v[34:37], v[10:13], v[188:191]
	v_max_f32_e32 v2, v42, v43
	v_mfma_f32_16x16x32_bf16 v[34:37], v[38:41], v[14:17], v[34:37]
	v_max_f32_e32 v4, v44, v45
	v_max_f32_e32 v7, v48, v48
	v_mfma_f32_16x16x32_bf16 v[38:41], v[102:105], v[10:13], v[188:191]
	v_max_f32_e32 v5, v7, v49
	v_max3_f32 v5, v46, v47, v5
	v_max3_f32 v2, v2, v4, v5
	v_mfma_f32_16x16x32_bf16 v[34:37], v[86:89], v[18:21], v[34:37]
	v_mov_b32_e32 v4, v2
	s_nop 1
	v_permlane16_swap_b32_e32 v2, v4
	v_mfma_f32_16x16x32_bf16 v[38:41], v[106:109], v[14:17], v[38:41]
	v_max_f32_e32 v2, v2, v4
	v_mfma_f32_16x16x32_bf16 v[34:37], v[90:93], v[22:25], v[34:37]
	v_mov_b32_e32 v4, v2
	s_nop 1
	v_permlane32_swap_b32_e32 v2, v4
	v_mfma_f32_16x16x32_bf16 v[38:41], v[110:113], v[18:21], v[38:41]
	v_max_f32_e32 v2, v2, v4
	v_mfma_f32_16x16x32_bf16 v[34:37], v[94:97], v[26:29], v[34:37]
	v_cmp_lt_f32_e32 vcc, s29, v2
	v_mfma_f32_16x16x32_bf16 v[38:41], v[114:117], v[22:25], v[38:41]
	v_mfma_f32_16x16x32_bf16 v[34:37], v[98:101], v[30:33], v[34:37]
	ds_read_b128 v[86:89], v150 offset:36864
	ds_read_b128 v[90:93], v150 offset:37888
	ds_read_b128 v[94:97], v150 offset:38912
	ds_read_b128 v[98:101], v150 offset:39936
	ds_read_b128 v[102:105], v150 offset:40960
	ds_read_b128 v[106:109], v150 offset:41984
	ds_read_b128 v[110:113], v150 offset:43008
	ds_read_b128 v[114:117], v150 offset:44032
	v_mfma_f32_16x16x32_bf16 v[38:41], v[180:183], v[26:29], v[38:41]
	v_mfma_f32_16x16x32_bf16 v[38:41], v[184:187], v[30:33], v[38:41]
	s_cbranch_vccz .LBB0_904
	v_max_f32_e32 v4, 0, v2
	v_exp_f32_e64 v2, -v4
	v_add_f32_e32 v135, v135, v4
	v_sub_f32_e32 v42, v42, v4
	v_sub_f32_e32 v43, v43, v4
	v_pk_mul_f32 v[80:81], v[80:81], v[2:3] op_sel_hi:[1,0]
	v_pk_mul_f32 v[78:79], v[78:79], v[2:3] op_sel_hi:[1,0]
	v_pk_mul_f32 v[76:77], v[76:77], v[2:3] op_sel_hi:[1,0]
	v_pk_mul_f32 v[74:75], v[74:75], v[2:3] op_sel_hi:[1,0]
	v_pk_mul_f32 v[72:73], v[72:73], v[2:3] op_sel_hi:[1,0]
	v_pk_mul_f32 v[70:71], v[70:71], v[2:3] op_sel_hi:[1,0]
	v_pk_mul_f32 v[68:69], v[68:69], v[2:3] op_sel_hi:[1,0]
	v_pk_mul_f32 v[66:67], v[66:67], v[2:3] op_sel_hi:[1,0]
	v_pk_mul_f32 v[64:65], v[64:65], v[2:3] op_sel_hi:[1,0]
	v_pk_mul_f32 v[62:63], v[62:63], v[2:3] op_sel_hi:[1,0]
	v_pk_mul_f32 v[60:61], v[60:61], v[2:3] op_sel_hi:[1,0]
	v_pk_mul_f32 v[58:59], v[58:59], v[2:3] op_sel_hi:[1,0]
	v_pk_mul_f32 v[56:57], v[56:57], v[2:3] op_sel_hi:[1,0]
	v_pk_mul_f32 v[54:55], v[54:55], v[2:3] op_sel_hi:[1,0]
	v_pk_mul_f32 v[52:53], v[52:53], v[2:3] op_sel_hi:[1,0]
	v_pk_mul_f32 v[50:51], v[50:51], v[2:3] op_sel_hi:[1,0]
	v_sub_f32_e32 v44, v44, v4
	v_sub_f32_e32 v45, v45, v4
	v_sub_f32_e32 v37, v37, v4
	v_sub_f32_e32 v36, v36, v4
	v_sub_f32_e32 v35, v35, v4
	v_sub_f32_e32 v34, v34, v4
	v_sub_f32_e32 v46, v46, v4
	v_sub_f32_e32 v47, v47, v4
	v_sub_f32_e32 v48, v48, v4
	v_sub_f32_e32 v49, v49, v4
	v_sub_f32_e32 v41, v41, v4
	v_sub_f32_e32 v40, v40, v4
	v_sub_f32_e32 v39, v39, v4
	v_sub_f32_e32 v38, v38, v4
	v_pk_mul_f32 v[84:85], v[84:85], v[2:3] op_sel_hi:[1,0]
	v_pk_mul_f32 v[82:83], v[82:83], v[2:3] op_sel_hi:[1,0]

.LBB0_910:
	v_xor_b32_e32 v188, 0x80000000, v135
	ds_read_b128 v[42:45], v155
	ds_read_b128 v[46:49], v156
	ds_read_b128 v[86:89], v157
	ds_read_b128 v[90:93], v158
	ds_read_b128 v[94:97], v159
	ds_read_b128 v[98:101], v160
	ds_read_b128 v[102:105], v161
	ds_read_b128 v[106:109], v162
	ds_read_b128 v[110:113], v163
	ds_read_b128 v[114:117], v164
	ds_read_b128 v[180:183], v165
	ds_read_b128 v[184:187], v166
	v_mov_b32_e32 v189, v188
	v_mov_b32_e32 v190, v188
	v_mov_b32_e32 v191, v188
	s_waitcnt lgkmcnt(0)
	s_nop 1
	v_mfma_f32_16x16x32_bf16 v[42:45], v[42:45], v[10:13], v[188:191]
	v_max_f32_e32 v2, v34, v35
	v_mfma_f32_16x16x32_bf16 v[42:45], v[46:49], v[14:17], v[42:45]
	v_max_f32_e32 v4, v36, v37
	v_max_f32_e32 v7, v40, v40
	v_mfma_f32_16x16x32_bf16 v[46:49], v[102:105], v[10:13], v[188:191]
	v_max_f32_e32 v5, v7, v41
	v_max3_f32 v5, v38, v39, v5
	v_max3_f32 v2, v2, v4, v5
	v_mfma_f32_16x16x32_bf16 v[42:45], v[86:89], v[18:21], v[42:45]
	v_mov_b32_e32 v4, v2
	s_nop 1
	v_permlane16_swap_b32_e32 v2, v4
	v_mfma_f32_16x16x32_bf16 v[46:49], v[106:109], v[14:17], v[46:49]
	v_max_f32_e32 v2, v2, v4
	v_mfma_f32_16x16x32_bf16 v[42:45], v[90:93], v[22:25], v[42:45]
	v_mov_b32_e32 v4, v2
	s_nop 1
	v_permlane32_swap_b32_e32 v2, v4
	v_mfma_f32_16x16x32_bf16 v[46:49], v[110:113], v[18:21], v[46:49]
	v_max_f32_e32 v2, v2, v4
	v_mfma_f32_16x16x32_bf16 v[42:45], v[94:97], v[26:29], v[42:45]
	v_cmp_lt_f32_e32 vcc, s29, v2
	v_mfma_f32_16x16x32_bf16 v[46:49], v[114:117], v[22:25], v[46:49]
	v_mfma_f32_16x16x32_bf16 v[42:45], v[98:101], v[30:33], v[42:45]
	ds_read_b128 v[86:89], v150 offset:61440
	ds_read_b128 v[90:93], v150 offset:62464
	ds_read_b128 v[94:97], v150 offset:63488
	ds_read_b128 v[98:101], v150 offset:64512
	ds_read_b128 v[102:105], v167
	ds_read_b128 v[106:109], v168
	ds_read_b128 v[110:113], v169
	ds_read_b128 v[114:117], v170
	v_mfma_f32_16x16x32_bf16 v[46:49], v[180:183], v[26:29], v[46:49]
	v_mfma_f32_16x16x32_bf16 v[46:49], v[184:187], v[30:33], v[46:49]
	s_cbranch_vccz .LBB0_912
	v_max_f32_e32 v4, 0, v2
	v_exp_f32_e64 v2, -v4
	v_add_f32_e32 v135, v135, v4
	v_sub_f32_e32 v37, v37, v4
	v_sub_f32_e32 v36, v36, v4
	v_pk_mul_f32 v[80:81], v[80:81], v[2:3] op_sel_hi:[1,0]
	v_pk_mul_f32 v[78:79], v[78:79], v[2:3] op_sel_hi:[1,0]
	v_pk_mul_f32 v[76:77], v[76:77], v[2:3] op_sel_hi:[1,0]
	v_pk_mul_f32 v[74:75], v[74:75], v[2:3] op_sel_hi:[1,0]
	v_pk_mul_f32 v[72:73], v[72:73], v[2:3] op_sel_hi:[1,0]
	v_pk_mul_f32 v[70:71], v[70:71], v[2:3] op_sel_hi:[1,0]
	v_pk_mul_f32 v[68:69], v[68:69], v[2:3] op_sel_hi:[1,0]
	v_pk_mul_f32 v[66:67], v[66:67], v[2:3] op_sel_hi:[1,0]
	v_pk_mul_f32 v[64:65], v[64:65], v[2:3] op_sel_hi:[1,0]
	v_pk_mul_f32 v[62:63], v[62:63], v[2:3] op_sel_hi:[1,0]
	v_pk_mul_f32 v[60:61], v[60:61], v[2:3] op_sel_hi:[1,0]
	v_pk_mul_f32 v[58:59], v[58:59], v[2:3] op_sel_hi:[1,0]
	v_pk_mul_f32 v[56:57], v[56:57], v[2:3] op_sel_hi:[1,0]
	v_pk_mul_f32 v[54:55], v[54:55], v[2:3] op_sel_hi:[1,0]
	v_pk_mul_f32 v[52:53], v[52:53], v[2:3] op_sel_hi:[1,0]
	v_pk_mul_f32 v[50:51], v[50:51], v[2:3] op_sel_hi:[1,0]
	v_sub_f32_e32 v35, v35, v4
	v_sub_f32_e32 v34, v34, v4
	v_sub_f32_e32 v45, v45, v4
	v_sub_f32_e32 v44, v44, v4
	v_sub_f32_e32 v43, v43, v4
	v_sub_f32_e32 v42, v42, v4
	v_sub_f32_e32 v41, v41, v4
	v_sub_f32_e32 v40, v40, v4
	v_sub_f32_e32 v39, v39, v4
	v_sub_f32_e32 v38, v38, v4
	v_sub_f32_e32 v49, v49, v4
	v_sub_f32_e32 v48, v48, v4
	v_sub_f32_e32 v47, v47, v4
	v_sub_f32_e32 v46, v46, v4
	v_pk_mul_f32 v[84:85], v[84:85], v[2:3] op_sel_hi:[1,0]
	v_pk_mul_f32 v[82:83], v[82:83], v[2:3] op_sel_hi:[1,0]

.LBB0_914:
	s_waitcnt lgkmcnt(0)
	s_barrier
	s_and_b64 vcc, exec, s[50:51]
	s_cbranch_vccnz .LBB0_916
	s_mov_b32 m0, s86
	v_xor_b32_e32 v38, 0x80000000, v135
	global_load_lds_dwordx4 v[142:143], off
	s_mov_b32 m0, s87
	v_mov_b32_e32 v39, v38
	global_load_lds_dwordx4 v[144:145], off
	s_mov_b32 m0, s47
	v_mov_b32_e32 v40, v38
	global_load_lds_dwordx4 v[146:147], off
	ds_read_b128 v[196:199], v150
	ds_read_b128 v[208:211], v150 offset:1024
	ds_read_b128 v[212:215], v150 offset:6144
	ds_read_b128 v[216:219], v150 offset:2048
	ds_read_b128 v[220:223], v150 offset:3072
	ds_read_b128 v[224:227], v150 offset:4096
	ds_read_b128 v[228:231], v150 offset:5120
	ds_read_b128 v[240:243], v150 offset:7168
	v_mov_b32_e32 v41, v38
	s_nop 0
	s_waitcnt lgkmcnt(7)
	s_nop 0
	v_mfma_f32_16x16x32_bf16 v[34:37], v[196:199], v[10:13], v[38:41]
	ds_read_b128 v[196:199], v150 offset:8192
	s_waitcnt lgkmcnt(7)
	v_mfma_f32_16x16x32_bf16 v[34:37], v[208:211], v[14:17], v[34:37]
	ds_read_b128 v[208:211], v150 offset:9216
	s_waitcnt lgkmcnt(7)
	v_mfma_f32_16x16x32_bf16 v[38:41], v[212:215], v[10:13], v[38:41]
	ds_read_b128 v[212:215], v150 offset:10240
	s_waitcnt lgkmcnt(7)
	v_mfma_f32_16x16x32_bf16 v[34:37], v[216:219], v[18:21], v[34:37]
	ds_read_b128 v[216:219], v150 offset:11264
	s_waitcnt lgkmcnt(7)
	v_mfma_f32_16x16x32_bf16 v[34:37], v[220:223], v[22:25], v[34:37]
	s_waitcnt lgkmcnt(6)
	v_mfma_f32_16x16x32_bf16 v[34:37], v[224:227], v[26:29], v[34:37]
	s_waitcnt lgkmcnt(5)
	v_mfma_f32_16x16x32_bf16 v[34:37], v[228:231], v[30:33], v[34:37]
	s_waitcnt lgkmcnt(4)
	v_mfma_f32_16x16x32_bf16 v[38:41], v[240:243], v[14:17], v[38:41]
	s_waitcnt lgkmcnt(3)
	v_mfma_f32_16x16x32_bf16 v[38:41], v[196:199], v[18:21], v[38:41]
	s_waitcnt lgkmcnt(2)
	v_mfma_f32_16x16x32_bf16 v[38:41], v[208:211], v[22:25], v[38:41]
	s_waitcnt lgkmcnt(1)
	v_mfma_f32_16x16x32_bf16 v[38:41], v[212:215], v[26:29], v[38:41]
	s_waitcnt lgkmcnt(0)
	v_mfma_f32_16x16x32_bf16 v[38:41], v[216:219], v[30:33], v[38:41]
.LBB0_916:
	v_max_f32_e32 v2, v42, v43
	v_max_f32_e32 v4, v44, v45
	v_max_f32_e32 v7, v48, v48
	v_max_f32_e32 v5, v7, v49
	ds_read_b128 v[86:89], v171
	ds_read_b128 v[90:93], v172
	ds_read_b128 v[94:97], v173
	ds_read_b128 v[98:101], v174
	ds_read_b128 v[102:105], v175
	ds_read_b128 v[106:109], v176
	ds_read_b128 v[110:113], v177
	ds_read_b128 v[114:117], v178
	v_max3_f32 v5, v46, v47, v5
	v_max3_f32 v2, v2, v4, v5
	v_mov_b32_e32 v4, v2
	s_nop 1
	v_permlane16_swap_b32_e32 v2, v4
	v_max_f32_e32 v2, v2, v4
	v_mov_b32_e32 v4, v2
	s_nop 1
	v_permlane32_swap_b32_e32 v2, v4
	v_max_f32_e32 v2, v2, v4
	v_cmp_lt_f32_e32 vcc, s29, v2
	s_cbranch_vccz .LBB0_894
	v_max_f32_e32 v4, 0, v2
	v_exp_f32_e64 v2, -v4
	v_sub_f32_e32 v5, v34, v4
	v_sub_f32_e32 v7, v35, v4
	v_sub_f32_e32 v8, v36, v4
	v_add_f32_e32 v135, v135, v4
	v_sub_f32_e32 v42, v42, v4
	v_sub_f32_e32 v43, v43, v4
	v_sub_f32_e32 v44, v44, v4
	v_sub_f32_e32 v45, v45, v4
	v_sub_f32_e32 v9, v37, v4
	v_cndmask_b32_e64 v36, v36, v8, s[24:25]
	v_cndmask_b32_e64 v35, v35, v7, s[24:25]
	v_cndmask_b32_e64 v34, v34, v5, s[24:25]
	v_sub_f32_e32 v46, v46, v4
	v_sub_f32_e32 v47, v47, v4
	v_sub_f32_e32 v48, v48, v4
	v_sub_f32_e32 v49, v49, v4
	v_sub_f32_e32 v5, v38, v4
	v_sub_f32_e32 v7, v39, v4
	v_sub_f32_e32 v8, v40, v4
	v_sub_f32_e32 v4, v41, v4
	v_pk_mul_f32 v[80:81], v[80:81], v[2:3] op_sel_hi:[1,0]
	v_pk_mul_f32 v[78:79], v[78:79], v[2:3] op_sel_hi:[1,0]
	v_pk_mul_f32 v[76:77], v[76:77], v[2:3] op_sel_hi:[1,0]
	v_pk_mul_f32 v[74:75], v[74:75], v[2:3] op_sel_hi:[1,0]
	v_pk_mul_f32 v[72:73], v[72:73], v[2:3] op_sel_hi:[1,0]
	v_pk_mul_f32 v[70:71], v[70:71], v[2:3] op_sel_hi:[1,0]
	v_pk_mul_f32 v[68:69], v[68:69], v[2:3] op_sel_hi:[1,0]
	v_pk_mul_f32 v[66:67], v[66:67], v[2:3] op_sel_hi:[1,0]
	v_pk_mul_f32 v[64:65], v[64:65], v[2:3] op_sel_hi:[1,0]
	v_pk_mul_f32 v[62:63], v[62:63], v[2:3] op_sel_hi:[1,0]
	v_pk_mul_f32 v[60:61], v[60:61], v[2:3] op_sel_hi:[1,0]
	v_pk_mul_f32 v[58:59], v[58:59], v[2:3] op_sel_hi:[1,0]
	v_pk_mul_f32 v[56:57], v[56:57], v[2:3] op_sel_hi:[1,0]
	v_pk_mul_f32 v[54:55], v[54:55], v[2:3] op_sel_hi:[1,0]
	v_pk_mul_f32 v[52:53], v[52:53], v[2:3] op_sel_hi:[1,0]
	v_pk_mul_f32 v[50:51], v[50:51], v[2:3] op_sel_hi:[1,0]
	v_cndmask_b32_e64 v37, v37, v9, s[24:25]
	v_cndmask_b32_e64 v41, v41, v4, s[24:25]
	v_cndmask_b32_e64 v40, v40, v8, s[24:25]
	v_cndmask_b32_e64 v39, v39, v7, s[24:25]
	v_cndmask_b32_e64 v38, v38, v5, s[24:25]
	v_pk_mul_f32 v[84:85], v[84:85], v[2:3] op_sel_hi:[1,0]
	v_pk_mul_f32 v[82:83], v[82:83], v[2:3] op_sel_hi:[1,0]
	s_branch .LBB0_894

.LBB0_1262:
	s_add_u32 s12, s12, s92
	s_addc_u32 s13, s13, s93
	s_add_u32 s12, s12, s14
	s_addc_u32 s13, s13, s15
	v_lshl_add_u64 v[8:9], s[12:13], 0, v[2:3]
	s_add_i32 m0, s95, 0x6000
	s_cmp_gt_u32 s79, 10
	global_load_lds_dwordx4 v[8:9], off
	s_cselect_b64 s[12:13], -1, 0
	s_add_i32 s35, s78, s79
	s_add_i32 s33, s35, 1
	s_cmp_ge_i32 s33, s47
	s_cselect_b64 s[14:15], -1, 0
	s_cmp_lt_i32 s33, s89
	s_cselect_b64 s[72:73], -1, 0
	s_and_b64 s[14:15], s[14:15], s[72:73]
	s_or_b64 s[74:75], s[12:13], s[14:15]
	v_cndmask_b32_e64 v7, 0, 1, s[74:75]
	v_cmp_ne_u32_e64 s[72:73], 1, v7
	s_andn2_b64 vcc, exec, s[74:75]
	s_cbranch_vccnz .LBB0_1264
	ds_read_b128 v[46:49], v75 offset:8192
	ds_read_b128 v[54:57], v75 offset:10240
	ds_read_b128 v[100:103], v75 offset:9216
	ds_read_b128 v[104:107], v75 offset:11264
	v_xor_b32_e32 v50, 0x80000000, v92
	v_mov_b32_e32 v51, v50
	v_mov_b32_e32 v52, v50
	v_mov_b32_e32 v53, v50
	s_waitcnt lgkmcnt(2)
	s_nop 0
	v_mfma_f32_16x16x32_bf16 v[46:49], v[46:49], v[10:13], v[50:53]
	v_mfma_f32_16x16x32_bf16 v[50:53], v[54:57], v[10:13], v[50:53]
	s_waitcnt lgkmcnt(1)
	v_mfma_f32_16x16x32_bf16 v[46:49], v[100:103], v[14:17], v[46:49]
	s_waitcnt lgkmcnt(0)
	v_mfma_f32_16x16x32_bf16 v[50:53], v[104:107], v[14:17], v[50:53]

.LBB0_1267:
	v_max_f32_e32 v7, v18, v19
	v_max_f32_e32 v8, v20, v21
	v_max_f32_e32 v93, v40, v40
	v_max_f32_e32 v9, v93, v41
	v_max3_f32 v9, v38, v39, v9
	v_max3_f32 v7, v7, v8, v9
	v_mov_b32_e32 v8, v7
	s_nop 1
	v_permlane16_swap_b32_e32 v7, v8
	v_max_f32_e32 v7, v7, v8
	v_mov_b32_e32 v8, v7
	s_nop 1
	v_permlane32_swap_b32_e32 v7, v8
	s_xor_b64 s[12:13], s[10:11], -1
	v_max_f32_e32 v7, v7, v8
	s_andn2_b64 vcc, exec, s[12:13]
	s_mov_b64 s[12:13], -1
	s_cbranch_vccnz .LBB0_1270
	v_cmp_lt_f32_e32 vcc, s29, v7
	s_cbranch_vccz .LBB0_1341
	v_max_f32_e32 v7, 0, v7

.LBB0_1282:
	s_cmp_gt_u32 s79, 9
	s_cselect_b64 s[16:17], -1, 0
	s_add_i32 s14, s35, 2
	s_cmp_ge_i32 s14, s47
	s_cselect_b64 s[12:13], -1, 0
	s_cmp_lt_i32 s14, s89
	s_cselect_b64 s[14:15], -1, 0
	s_and_b64 s[12:13], s[12:13], s[14:15]
	s_or_b64 s[76:77], s[16:17], s[12:13]
	v_cndmask_b32_e64 v7, 0, 1, s[76:77]
	v_cmp_ne_u32_e64 s[74:75], 1, v7
	s_andn2_b64 vcc, exec, s[76:77]
	s_cbranch_vccnz .LBB0_1284
	ds_read_b128 v[18:21], v75 offset:16384
	ds_read_b128 v[54:57], v75 offset:18432
	ds_read_b128 v[100:103], v75 offset:17408
	ds_read_b128 v[104:107], v75 offset:19456
	v_xor_b32_e32 v38, 0x80000000, v92
	v_mov_b32_e32 v39, v38
	v_mov_b32_e32 v40, v38
	v_mov_b32_e32 v41, v38
	s_waitcnt lgkmcnt(2)
	s_nop 0
	v_mfma_f32_16x16x32_bf16 v[18:21], v[18:21], v[10:13], v[38:41]
	v_mfma_f32_16x16x32_bf16 v[38:41], v[54:57], v[10:13], v[38:41]
	s_waitcnt lgkmcnt(1)
	v_mfma_f32_16x16x32_bf16 v[18:21], v[100:103], v[14:17], v[18:21]
	s_waitcnt lgkmcnt(0)
	v_mfma_f32_16x16x32_bf16 v[38:41], v[104:107], v[14:17], v[38:41]

.LBB0_1287:
	v_max_f32_e32 v7, v46, v47
	v_max_f32_e32 v8, v48, v49
	v_max_f32_e32 v93, v52, v52
	v_max_f32_e32 v9, v93, v53
	v_max3_f32 v9, v50, v51, v9
	v_max3_f32 v7, v7, v8, v9
	v_mov_b32_e32 v8, v7
	s_nop 1
	v_permlane16_swap_b32_e32 v7, v8
	v_max_f32_e32 v7, v7, v8
	v_mov_b32_e32 v8, v7
	s_nop 1
	v_permlane32_swap_b32_e32 v7, v8
	s_xor_b64 s[12:13], s[10:11], -1
	v_max_f32_e32 v7, v7, v8
	s_andn2_b64 vcc, exec, s[12:13]
	s_mov_b64 s[12:13], -1
	s_cbranch_vccnz .LBB0_1290
	v_cmp_lt_f32_e32 vcc, s29, v7
	s_cbranch_vccz .LBB0_1342
	v_max_f32_e32 v7, 0, v7

.LBB0_1306:
	s_add_i32 s14, s35, 3
	s_cmp_ge_i32 s14, s47
	s_cselect_b64 s[12:13], -1, 0
	s_cmp_lt_i32 s14, s89
	s_cselect_b64 s[14:15], -1, 0
	s_and_b64 s[12:13], s[12:13], s[14:15]
	s_or_b64 s[76:77], s[16:17], s[12:13]
	v_cndmask_b32_e64 v7, 0, 1, s[76:77]
	v_cmp_ne_u32_e64 s[72:73], 1, v7
	s_andn2_b64 vcc, exec, s[76:77]
	s_cbranch_vccnz .LBB0_1308
	ds_read_b128 v[46:49], v75 offset:24576
	ds_read_b128 v[54:57], v75 offset:26624
	ds_read_b128 v[100:103], v75 offset:25600
	ds_read_b128 v[104:107], v75 offset:27648
	v_xor_b32_e32 v50, 0x80000000, v92
	v_mov_b32_e32 v51, v50
	v_mov_b32_e32 v52, v50
	v_mov_b32_e32 v53, v50
	s_waitcnt lgkmcnt(2)
	s_nop 0
	v_mfma_f32_16x16x32_bf16 v[46:49], v[46:49], v[10:13], v[50:53]
	v_mfma_f32_16x16x32_bf16 v[50:53], v[54:57], v[10:13], v[50:53]
	s_waitcnt lgkmcnt(1)
	v_mfma_f32_16x16x32_bf16 v[46:49], v[100:103], v[14:17], v[46:49]
	s_waitcnt lgkmcnt(0)
	v_mfma_f32_16x16x32_bf16 v[50:53], v[104:107], v[14:17], v[50:53]

.LBB0_1328:
	s_cmp_gt_u32 s33, 10
	s_cselect_b64 s[14:15], -1, 0
	s_add_i32 s35, s35, 4
	s_cmp_ge_i32 s35, s47
	s_cselect_b64 s[16:17], -1, 0
	s_cmp_lt_i32 s35, s89
	s_cselect_b64 s[74:75], -1, 0
	s_and_b64 s[16:17], s[16:17], s[74:75]
	s_or_b64 s[14:15], s[14:15], s[16:17]
	s_and_b64 s[16:17], s[12:13], s[14:15]
	s_andn2_b64 vcc, exec, s[16:17]
	s_cbranch_vccnz .LBB0_1330
	ds_read_b128 v[18:21], v75
	ds_read_b128 v[54:57], v75 offset:2048
	ds_read_b128 v[100:103], v75 offset:1024
	ds_read_b128 v[104:107], v75 offset:3072
	v_xor_b32_e32 v38, 0x80000000, v92
	v_mov_b32_e32 v39, v38
	v_mov_b32_e32 v40, v38
	v_mov_b32_e32 v41, v38
	s_waitcnt lgkmcnt(2)
	s_nop 0
	v_mfma_f32_16x16x32_bf16 v[18:21], v[18:21], v[10:13], v[38:41]
	v_mfma_f32_16x16x32_bf16 v[38:41], v[54:57], v[10:13], v[38:41]
	s_waitcnt lgkmcnt(1)
	v_mfma_f32_16x16x32_bf16 v[18:21], v[100:103], v[14:17], v[18:21]
	s_waitcnt lgkmcnt(0)
	v_mfma_f32_16x16x32_bf16 v[38:41], v[104:107], v[14:17], v[38:41]

.LBB0_1350:
	s_waitcnt vmcnt(1)
	s_lshl_b32 s90, s12, s23
	s_waitcnt lgkmcnt(0)
	s_barrier
	v_lshl_add_u64 v[8:9], v[138:139], 0, s[90:91]
	s_add_i32 m0, s24, 0x6000
	ds_read_b128 v[42:45], v5 offset:8192
	ds_read_b128 v[98:101], v5 offset:9216
	ds_read_b128 v[102:105], v5 offset:10240
	ds_read_b128 v[110:113], v5 offset:11264
	global_load_lds_dwordx4 v[8:9], off
	v_xor_b32_e32 v46, 0x80000000, v140
	v_mov_b32_e32 v47, v46
	v_mov_b32_e32 v48, v46
	v_mov_b32_e32 v49, v46
	s_waitcnt lgkmcnt(0)
	s_nop 1
	v_mfma_f32_16x16x32_bf16 v[54:57], v[42:45], v[10:13], v[46:49]
	v_max_f32_e32 v7, v34, v35
	v_mfma_f32_16x16x32_bf16 v[46:49], v[102:105], v[10:13], v[46:49]
	v_max_f32_e32 v8, v36, v37
	s_and_b64 vcc, exec, s[10:11]
	v_mfma_f32_16x16x32_bf16 v[58:61], v[98:101], v[18:21], v[54:57]
	v_mfma_f32_16x16x32_bf16 v[54:57], v[110:113], v[18:21], v[46:49]
	s_nop 2
	s_nop 0
	v_xor_b32_e32 v46, 0x80000000, v1
	v_mov_b32_e32 v47, v46
	v_mov_b32_e32 v48, v46
	v_mov_b32_e32 v49, v46
	s_nop 1
	v_mfma_f32_16x16x32_bf16 v[42:45], v[42:45], v[14:17], v[46:49]
	v_mfma_f32_16x16x32_bf16 v[42:45], v[98:101], v[22:25], v[42:45]
	v_max_f32_e32 v98, v40, v40
	v_max_f32_e32 v9, v98, v41
	v_max3_f32 v9, v38, v39, v9
	v_mfma_f32_16x16x32_bf16 v[46:49], v[102:105], v[14:17], v[46:49]
	v_max3_f32 v7, v7, v8, v9
	v_mov_b32_e32 v8, v7
	s_nop 1
	v_permlane16_swap_b32_e32 v7, v8
	ds_read_b128 v[102:105], v5 offset:4096
	ds_read_b128 v[106:109], v5 offset:5120
	v_mfma_f32_16x16x32_bf16 v[46:49], v[110:113], v[22:25], v[46:49]
	ds_read_b128 v[110:113], v5 offset:6144
	ds_read_b128 v[114:117], v5 offset:7168
	v_max_f32_e32 v7, v7, v8
	v_mov_b32_e32 v8, v7
	s_nop 1
	v_permlane32_swap_b32_e32 v7, v8
	v_max_f32_e32 v7, v7, v8
	s_cbranch_vccnz .LBB0_1353
	v_cmp_lt_f32_e32 vcc, s29, v7
	s_cbranch_vccz .LBB0_1384
	v_max_f32_e32 v7, 0, v7

.LBB0_1355:
	v_exp_f32_e32 v7, v34
	v_exp_f32_e32 v8, v35
	v_exp_f32_e32 v9, v36
	v_exp_f32_e32 v35, v37
	v_exp_f32_e32 v36, v38
	v_exp_f32_e32 v37, v39
	v_exp_f32_e32 v38, v40
	v_exp_f32_e32 v39, v41
	v_cvt_pk_bf16_f32 v34, v7, v8
	v_cvt_pk_bf16_f32 v35, v9, v35
	v_mov_b32_e32 v7, v6
	v_mov_b32_e32 v8, v6
	v_mov_b32_e32 v9, v6
	v_cvt_pk_bf16_f32 v36, v36, v37
	v_cvt_pk_bf16_f32 v37, v38, v39
	s_xor_b64 s[12:13], s[10:11], -1
	s_andn2_b64 vcc, exec, s[12:13]
	s_waitcnt lgkmcnt(0)
	v_mfma_f32_16x16x32_bf16 v[98:101], v[102:105], v[34:37], v[74:77]
	v_mfma_f32_16x16x32_bf16 v[74:77], v[114:117], v[34:37], v[78:81]
	v_mfma_f32_16x16x32_bf16 v[78:81], v[6:9], v[34:37], v[94:97]
	v_max_f32_e32 v7, v26, v27
	v_mfma_f32_16x16x32_bf16 v[90:93], v[106:109], v[34:37], v[90:93]
	v_max_f32_e32 v8, v28, v29
	v_mfma_f32_16x16x32_bf16 v[82:85], v[110:113], v[34:37], v[82:85]
	v_max_f32_e32 v34, v32, v32
	v_max_f32_e32 v9, v34, v33
	v_max3_f32 v9, v30, v31, v9
	v_max3_f32 v7, v7, v8, v9
	v_mov_b32_e32 v8, v7
	s_nop 1
	v_permlane16_swap_b32_e32 v7, v8
	v_max_f32_e32 v7, v7, v8
	v_mov_b32_e32 v8, v7
	s_nop 1
	v_permlane32_swap_b32_e32 v7, v8
	v_max_f32_e32 v7, v7, v8
	v_cndmask_b32_e64 v8, 0, 1, s[12:13]
	v_cmp_ne_u32_e64 s[50:51], 1, v8
	s_mov_b64 s[12:13], -1
	s_cbranch_vccnz .LBB0_1358
	v_cmp_lt_f32_e32 vcc, s29, v7
	s_cbranch_vccz .LBB0_1385
	v_max_f32_e32 v7, 0, v7

.LBB0_1362:
	ds_read_b128 v[26:29], v5 offset:16384
	ds_read_b128 v[30:33], v5 offset:17408
	ds_read_b128 v[86:89], v5 offset:18432
	ds_read_b128 v[94:97], v5 offset:19456
	v_xor_b32_e32 v38, 0x80000000, v140
	v_xor_b32_e32 v106, 0x80000000, v1
	v_mov_b32_e32 v39, v38
	v_mov_b32_e32 v40, v38
	v_mov_b32_e32 v41, v38
	v_mov_b32_e32 v107, v106
	v_mov_b32_e32 v108, v106
	v_mov_b32_e32 v109, v106
	s_waitcnt lgkmcnt(0)
	v_mfma_f32_16x16x32_bf16 v[34:37], v[26:29], v[10:13], v[38:41]
	v_max_f32_e32 v7, v58, v59
	v_mfma_f32_16x16x32_bf16 v[26:29], v[26:29], v[14:17], v[106:109]
	v_max_f32_e32 v8, v60, v61
	v_mfma_f32_16x16x32_bf16 v[34:37], v[30:33], v[18:21], v[34:37]
	v_mfma_f32_16x16x32_bf16 v[38:41], v[86:89], v[10:13], v[38:41]
	v_mfma_f32_16x16x32_bf16 v[26:29], v[30:33], v[22:25], v[26:29]
	v_mfma_f32_16x16x32_bf16 v[30:33], v[86:89], v[14:17], v[106:109]
	v_max_f32_e32 v86, v56, v56
	v_max_f32_e32 v9, v86, v57
	v_max3_f32 v9, v54, v55, v9
	v_max3_f32 v7, v7, v8, v9
	v_mov_b32_e32 v8, v7
	s_nop 1
	v_permlane16_swap_b32_e32 v7, v8
	ds_read_b128 v[106:109], v5 offset:12288
	ds_read_b128 v[110:113], v5 offset:13312
	ds_read_b128 v[114:117], v5 offset:14336
	ds_read_b128 v[118:121], v5 offset:15360
	v_max_f32_e32 v7, v7, v8
	v_mov_b32_e32 v8, v7
	v_mfma_f32_16x16x32_bf16 v[38:41], v[94:97], v[18:21], v[38:41]
	s_nop 0
	v_permlane32_swap_b32_e32 v7, v8
	v_mfma_f32_16x16x32_bf16 v[30:33], v[94:97], v[22:25], v[30:33]
	v_max_f32_e32 v7, v7, v8
	v_cmp_lt_f32_e32 vcc, s29, v7
	s_cbranch_vccz .LBB0_1364
	v_max_f32_e32 v7, 0, v7
	v_exp_f32_e64 v8, -v7
	v_add_f32_e32 v140, v140, v7
	v_sub_f32_e32 v58, v58, v7
	v_sub_f32_e32 v59, v59, v7
	v_pk_mul_f32 v[80:81], v[80:81], v[8:9] op_sel_hi:[1,0]
	v_pk_mul_f32 v[78:79], v[78:79], v[8:9] op_sel_hi:[1,0]
	v_pk_mul_f32 v[100:101], v[100:101], v[8:9] op_sel_hi:[1,0]
	v_pk_mul_f32 v[98:99], v[98:99], v[8:9] op_sel_hi:[1,0]
	v_pk_mul_f32 v[92:93], v[92:93], v[8:9] op_sel_hi:[1,0]
	v_pk_mul_f32 v[90:91], v[90:91], v[8:9] op_sel_hi:[1,0]
	v_pk_mul_f32 v[84:85], v[84:85], v[8:9] op_sel_hi:[1,0]
	v_pk_mul_f32 v[82:83], v[82:83], v[8:9] op_sel_hi:[1,0]
	v_pk_mul_f32 v[76:77], v[76:77], v[8:9] op_sel_hi:[1,0]
	v_pk_mul_f32 v[74:75], v[74:75], v[8:9] op_sel_hi:[1,0]
	v_sub_f32_e32 v60, v60, v7
	v_sub_f32_e32 v61, v61, v7
	v_sub_f32_e32 v37, v37, v7
	v_sub_f32_e32 v36, v36, v7
	v_sub_f32_e32 v35, v35, v7
	v_sub_f32_e32 v34, v34, v7
	v_sub_f32_e32 v54, v54, v7
	v_sub_f32_e32 v55, v55, v7
	v_sub_f32_e32 v56, v56, v7
	v_sub_f32_e32 v57, v57, v7
	v_sub_f32_e32 v41, v41, v7
	v_sub_f32_e32 v40, v40, v7
	v_sub_f32_e32 v39, v39, v7
	v_sub_f32_e32 v38, v38, v7
.LBB0_1364:
	v_exp_f32_e32 v7, v58
	v_exp_f32_e32 v8, v59
	v_exp_f32_e32 v9, v60
	v_exp_f32_e32 v58, v61
	v_exp_f32_e32 v59, v54
	v_exp_f32_e32 v60, v55
	v_exp_f32_e32 v61, v56
	v_exp_f32_e32 v57, v57
	v_cvt_pk_bf16_f32 v54, v7, v8
	v_cvt_pk_bf16_f32 v55, v9, v58
	v_mov_b32_e32 v7, v6
	v_mov_b32_e32 v8, v6
	v_mov_b32_e32 v9, v6
	v_cvt_pk_bf16_f32 v56, v59, v60
	v_cvt_pk_bf16_f32 v57, v61, v57
	s_waitcnt lgkmcnt(0)
	s_nop 0
	v_mfma_f32_16x16x32_bf16 v[94:97], v[106:109], v[54:57], v[98:101]
	v_mfma_f32_16x16x32_bf16 v[90:93], v[110:113], v[54:57], v[90:93]
	v_mfma_f32_16x16x32_bf16 v[86:89], v[114:117], v[54:57], v[82:85]
	v_mfma_f32_16x16x32_bf16 v[82:85], v[118:121], v[54:57], v[74:77]
	v_mfma_f32_16x16x32_bf16 v[78:81], v[6:9], v[54:57], v[78:81]
	v_max_f32_e32 v54, v42, v43
	v_max_f32_e32 v55, v44, v45
	v_max_f32_e32 v57, v48, v48
	v_max_f32_e32 v56, v57, v49
	v_max3_f32 v56, v46, v47, v56
	v_max3_f32 v54, v54, v55, v56
	v_mov_b32_e32 v55, v54
	s_nop 1
	v_permlane16_swap_b32_e32 v54, v55
	v_max_f32_e32 v54, v54, v55
	v_mov_b32_e32 v55, v54
	s_nop 1
	v_permlane32_swap_b32_e32 v54, v55
	v_max_f32_e32 v54, v54, v55
	v_cmp_lt_f32_e32 vcc, s29, v54
	s_cbranch_vccz .LBB0_1366
	v_max_f32_e32 v55, 0, v54
	v_exp_f32_e64 v54, -v55
	v_add_f32_e32 v1, v1, v55
	v_sub_f32_e32 v42, v42, v55
	v_sub_f32_e32 v43, v43, v55
	v_pk_mul_f32 v[104:105], v[104:105], v[54:55] op_sel_hi:[1,0]
	v_pk_mul_f32 v[102:103], v[102:103], v[54:55] op_sel_hi:[1,0]
	v_pk_mul_f32 v[72:73], v[72:73], v[54:55] op_sel_hi:[1,0]
	v_pk_mul_f32 v[70:71], v[70:71], v[54:55] op_sel_hi:[1,0]
	v_pk_mul_f32 v[68:69], v[68:69], v[54:55] op_sel_hi:[1,0]
	v_pk_mul_f32 v[66:67], v[66:67], v[54:55] op_sel_hi:[1,0]
	v_pk_mul_f32 v[64:65], v[64:65], v[54:55] op_sel_hi:[1,0]
	v_pk_mul_f32 v[62:63], v[62:63], v[54:55] op_sel_hi:[1,0]
	v_pk_mul_f32 v[52:53], v[52:53], v[54:55] op_sel_hi:[1,0]
	v_pk_mul_f32 v[50:51], v[50:51], v[54:55] op_sel_hi:[1,0]
	v_sub_f32_e32 v44, v44, v55
	v_sub_f32_e32 v45, v45, v55
	v_sub_f32_e32 v29, v29, v55
	v_sub_f32_e32 v28, v28, v55
	v_sub_f32_e32 v27, v27, v55
	v_sub_f32_e32 v26, v26, v55
	v_sub_f32_e32 v46, v46, v55
	v_sub_f32_e32 v47, v47, v55
	v_sub_f32_e32 v48, v48, v55
	v_sub_f32_e32 v49, v49, v55
	v_sub_f32_e32 v33, v33, v55
	v_sub_f32_e32 v32, v32, v55
	v_sub_f32_e32 v31, v31, v55
	v_sub_f32_e32 v30, v30, v55

.LBB0_1372:
	ds_read_b128 v[42:45], v5 offset:24576
	ds_read_b128 v[46:49], v5 offset:25600
	ds_read_b128 v[98:101], v5 offset:26624
	ds_read_b128 v[102:105], v5 offset:27648
	v_xor_b32_e32 v54, 0x80000000, v140
	v_xor_b32_e32 v106, 0x80000000, v1
	v_mov_b32_e32 v55, v54
	v_mov_b32_e32 v56, v54
	v_mov_b32_e32 v57, v54
	v_mov_b32_e32 v107, v106
	v_mov_b32_e32 v108, v106
	v_mov_b32_e32 v109, v106
	s_waitcnt lgkmcnt(0)
	v_mfma_f32_16x16x32_bf16 v[50:53], v[42:45], v[10:13], v[54:57]
	v_max_f32_e32 v7, v34, v35
	v_mfma_f32_16x16x32_bf16 v[42:45], v[42:45], v[14:17], v[106:109]
	v_max_f32_e32 v8, v36, v37
	v_mfma_f32_16x16x32_bf16 v[50:53], v[46:49], v[18:21], v[50:53]
	v_mfma_f32_16x16x32_bf16 v[54:57], v[98:101], v[10:13], v[54:57]
	v_mfma_f32_16x16x32_bf16 v[46:49], v[46:49], v[22:25], v[42:45]
	v_mfma_f32_16x16x32_bf16 v[42:45], v[98:101], v[14:17], v[106:109]
	v_max_f32_e32 v98, v40, v40
	v_max_f32_e32 v9, v98, v41
	v_max3_f32 v9, v38, v39, v9
	v_max3_f32 v7, v7, v8, v9
	v_mov_b32_e32 v8, v7
	s_nop 1
	v_permlane16_swap_b32_e32 v7, v8
	ds_read_b128 v[106:109], v5 offset:20480
	ds_read_b128 v[110:113], v5 offset:21504
	ds_read_b128 v[122:125], v5 offset:22528
	ds_read_b128 v[126:129], v5 offset:23552
	v_max_f32_e32 v7, v7, v8
	v_mov_b32_e32 v8, v7
	v_mfma_f32_16x16x32_bf16 v[54:57], v[102:105], v[18:21], v[54:57]
	s_nop 0
	v_permlane32_swap_b32_e32 v7, v8
	v_mfma_f32_16x16x32_bf16 v[42:45], v[102:105], v[22:25], v[42:45]
	v_max_f32_e32 v7, v7, v8
	v_cmp_lt_f32_e32 vcc, s29, v7
	s_cbranch_vccz .LBB0_1374
	v_max_f32_e32 v7, 0, v7
	v_exp_f32_e64 v8, -v7
	v_add_f32_e32 v140, v140, v7
	v_sub_f32_e32 v37, v37, v7
	v_sub_f32_e32 v36, v36, v7
	v_pk_mul_f32 v[80:81], v[80:81], v[8:9] op_sel_hi:[1,0]
	v_pk_mul_f32 v[78:79], v[78:79], v[8:9] op_sel_hi:[1,0]
	v_pk_mul_f32 v[96:97], v[96:97], v[8:9] op_sel_hi:[1,0]
	v_pk_mul_f32 v[94:95], v[94:95], v[8:9] op_sel_hi:[1,0]
	v_pk_mul_f32 v[92:93], v[92:93], v[8:9] op_sel_hi:[1,0]
	v_pk_mul_f32 v[90:91], v[90:91], v[8:9] op_sel_hi:[1,0]
	v_pk_mul_f32 v[88:89], v[88:89], v[8:9] op_sel_hi:[1,0]
	v_pk_mul_f32 v[86:87], v[86:87], v[8:9] op_sel_hi:[1,0]
	v_pk_mul_f32 v[84:85], v[84:85], v[8:9] op_sel_hi:[1,0]
	v_pk_mul_f32 v[82:83], v[82:83], v[8:9] op_sel_hi:[1,0]
	v_sub_f32_e32 v35, v35, v7
	v_sub_f32_e32 v34, v34, v7
	v_sub_f32_e32 v53, v53, v7
	v_sub_f32_e32 v52, v52, v7
	v_sub_f32_e32 v51, v51, v7
	v_sub_f32_e32 v50, v50, v7
	v_sub_f32_e32 v41, v41, v7
	v_sub_f32_e32 v40, v40, v7
	v_sub_f32_e32 v39, v39, v7
	v_sub_f32_e32 v38, v38, v7
	v_sub_f32_e32 v57, v57, v7
	v_sub_f32_e32 v56, v56, v7
	v_sub_f32_e32 v55, v55, v7
	v_sub_f32_e32 v54, v54, v7
.LBB0_1374:
	v_exp_f32_e32 v7, v34
	v_exp_f32_e32 v8, v35
	v_exp_f32_e32 v9, v36
	v_exp_f32_e32 v98, v37
	v_exp_f32_e32 v99, v38
	v_exp_f32_e32 v100, v39
	v_exp_f32_e32 v101, v40
	v_exp_f32_e32 v105, v41
	v_cvt_pk_bf16_f32 v102, v7, v8
	v_cvt_pk_bf16_f32 v103, v9, v98
	v_mov_b32_e32 v7, v6
	v_mov_b32_e32 v8, v6
	v_mov_b32_e32 v9, v6
	v_cvt_pk_bf16_f32 v104, v99, v100
	v_cvt_pk_bf16_f32 v105, v101, v105
	s_waitcnt lgkmcnt(0)
	s_nop 0
	v_mfma_f32_16x16x32_bf16 v[98:101], v[106:109], v[102:105], v[94:97]
	v_mfma_f32_16x16x32_bf16 v[90:93], v[110:113], v[102:105], v[90:93]
	v_mfma_f32_16x16x32_bf16 v[94:97], v[122:125], v[102:105], v[86:89]
	v_mfma_f32_16x16x32_bf16 v[86:89], v[126:129], v[102:105], v[82:85]
	v_mfma_f32_16x16x32_bf16 v[102:105], v[6:9], v[102:105], v[78:81]
	s_nop 2
	v_max_f32_e32 v78, v26, v27
	v_max_f32_e32 v79, v28, v29
	v_max_f32_e32 v81, v32, v32
	v_max_f32_e32 v80, v81, v33
	v_max3_f32 v80, v30, v31, v80
	v_max3_f32 v78, v78, v79, v80
	v_mov_b32_e32 v79, v78
	s_nop 1
	v_permlane16_swap_b32_e32 v78, v79
	v_max_f32_e32 v78, v78, v79
	v_mov_b32_e32 v79, v78
	s_nop 1
	v_permlane32_swap_b32_e32 v78, v79
	v_max_f32_e32 v78, v78, v79
	v_cmp_lt_f32_e32 vcc, s29, v78
	s_cbranch_vccz .LBB0_1376
	v_max_f32_e32 v79, 0, v78
	v_exp_f32_e64 v78, -v79
	v_add_f32_e32 v1, v1, v79
	v_sub_f32_e32 v29, v29, v79
	v_sub_f32_e32 v28, v28, v79
	v_pk_mul_f32 v[60:61], v[60:61], v[78:79] op_sel_hi:[1,0]
	v_pk_mul_f32 v[58:59], v[58:59], v[78:79] op_sel_hi:[1,0]
	v_pk_mul_f32 v[76:77], v[76:77], v[78:79] op_sel_hi:[1,0]
	v_pk_mul_f32 v[74:75], v[74:75], v[78:79] op_sel_hi:[1,0]
	v_pk_mul_f32 v[72:73], v[72:73], v[78:79] op_sel_hi:[1,0]
	v_pk_mul_f32 v[70:71], v[70:71], v[78:79] op_sel_hi:[1,0]
	v_pk_mul_f32 v[68:69], v[68:69], v[78:79] op_sel_hi:[1,0]
	v_pk_mul_f32 v[66:67], v[66:67], v[78:79] op_sel_hi:[1,0]
	v_pk_mul_f32 v[64:65], v[64:65], v[78:79] op_sel_hi:[1,0]
	v_pk_mul_f32 v[62:63], v[62:63], v[78:79] op_sel_hi:[1,0]
	v_sub_f32_e32 v27, v27, v79
	v_sub_f32_e32 v26, v26, v79
	v_sub_f32_e32 v49, v49, v79
	v_sub_f32_e32 v48, v48, v79
	v_sub_f32_e32 v47, v47, v79
	v_sub_f32_e32 v46, v46, v79
	v_sub_f32_e32 v33, v33, v79
	v_sub_f32_e32 v32, v32, v79
	v_sub_f32_e32 v31, v31, v79
	v_sub_f32_e32 v30, v30, v79
	v_sub_f32_e32 v45, v45, v79
	v_sub_f32_e32 v44, v44, v79
	v_sub_f32_e32 v43, v43, v79
	v_sub_f32_e32 v42, v42, v79

.LBB0_1380:
	v_max_f32_e32 v7, v50, v51
	v_max_f32_e32 v8, v52, v53
	v_max_f32_e32 v70, v56, v56
	v_max_f32_e32 v9, v70, v57
	v_max3_f32 v9, v54, v55, v9
	v_max3_f32 v7, v7, v8, v9
	v_mov_b32_e32 v8, v7
	s_nop 1
	v_permlane16_swap_b32_e32 v7, v8
	ds_read_b128 v[62:65], v5 offset:28672
	ds_read_b128 v[66:69], v5 offset:29696
	ds_read_b128 v[122:125], v5 offset:30720
	ds_read_b128 v[126:129], v5 offset:31744
	v_max_f32_e32 v7, v7, v8
	v_mov_b32_e32 v8, v7
	s_nop 1
	v_permlane32_swap_b32_e32 v7, v8
	v_max_f32_e32 v7, v7, v8
	v_cmp_lt_f32_e32 vcc, s29, v7
	s_cbranch_vccz .LBB0_1382
	v_max_f32_e32 v7, 0, v7
	v_exp_f32_e64 v8, -v7
	v_sub_f32_e32 v70, v36, v7
	v_add_f32_e32 v140, v140, v7
	v_sub_f32_e32 v50, v50, v7
	v_pk_mul_f32 v[104:105], v[104:105], v[8:9] op_sel_hi:[1,0]
	v_pk_mul_f32 v[102:103], v[102:103], v[8:9] op_sel_hi:[1,0]
	v_pk_mul_f32 v[100:101], v[100:101], v[8:9] op_sel_hi:[1,0]
	v_pk_mul_f32 v[98:99], v[98:99], v[8:9] op_sel_hi:[1,0]
	v_pk_mul_f32 v[92:93], v[92:93], v[8:9] op_sel_hi:[1,0]
	v_pk_mul_f32 v[90:91], v[90:91], v[8:9] op_sel_hi:[1,0]
	v_pk_mul_f32 v[96:97], v[96:97], v[8:9] op_sel_hi:[1,0]
	v_pk_mul_f32 v[94:95], v[94:95], v[8:9] op_sel_hi:[1,0]
	v_pk_mul_f32 v[88:89], v[88:89], v[8:9] op_sel_hi:[1,0]
	v_pk_mul_f32 v[86:87], v[86:87], v[8:9] op_sel_hi:[1,0]
	v_sub_f32_e32 v8, v34, v7
	v_sub_f32_e32 v9, v35, v7
	v_sub_f32_e32 v51, v51, v7
	v_sub_f32_e32 v52, v52, v7
	v_sub_f32_e32 v53, v53, v7
	v_sub_f32_e32 v71, v37, v7
	v_cndmask_b32_e64 v36, v36, v70, s[10:11]
	v_cndmask_b32_e64 v35, v35, v9, s[10:11]
	v_cndmask_b32_e64 v34, v34, v8, s[10:11]
	v_sub_f32_e32 v54, v54, v7
	v_sub_f32_e32 v55, v55, v7
	v_sub_f32_e32 v56, v56, v7
	v_sub_f32_e32 v57, v57, v7
	v_sub_f32_e32 v8, v38, v7
	v_sub_f32_e32 v9, v39, v7
	v_sub_f32_e32 v70, v40, v7
	v_sub_f32_e32 v7, v41, v7
	v_cndmask_b32_e64 v37, v37, v71, s[10:11]
	v_cndmask_b32_e64 v41, v41, v7, s[10:11]
	v_cndmask_b32_e64 v40, v40, v70, s[10:11]
	v_cndmask_b32_e64 v39, v39, v9, s[10:11]
	v_cndmask_b32_e64 v38, v38, v8, s[10:11]
.LBB0_1382:
	v_exp_f32_e32 v7, v50
	v_exp_f32_e32 v8, v51
	v_exp_f32_e32 v9, v52
	v_exp_f32_e32 v51, v53
	v_exp_f32_e32 v52, v54
	v_exp_f32_e32 v53, v55
	v_exp_f32_e32 v54, v56
	v_exp_f32_e32 v55, v57
	v_cvt_pk_bf16_f32 v50, v7, v8
	v_cvt_pk_bf16_f32 v51, v9, v51
	v_mov_b32_e32 v7, v6
	v_mov_b32_e32 v8, v6
	v_mov_b32_e32 v9, v6
	v_cvt_pk_bf16_f32 v52, v52, v53
	v_cvt_pk_bf16_f32 v53, v54, v55
	s_waitcnt lgkmcnt(0)
	s_nop 0
	v_mfma_f32_16x16x32_bf16 v[74:77], v[62:65], v[50:53], v[98:101]
	v_mfma_f32_16x16x32_bf16 v[90:93], v[66:69], v[50:53], v[90:93]
	v_mfma_f32_16x16x32_bf16 v[82:85], v[122:125], v[50:53], v[94:97]
	v_mfma_f32_16x16x32_bf16 v[78:81], v[126:129], v[50:53], v[86:89]
	v_mfma_f32_16x16x32_bf16 v[94:97], v[6:9], v[50:53], v[102:105]
	v_max_f32_e32 v50, v46, v47
	v_max_f32_e32 v51, v48, v49
	v_max_f32_e32 v53, v44, v44
	v_max_f32_e32 v52, v53, v45
	v_max3_f32 v52, v42, v43, v52
	v_max3_f32 v50, v50, v51, v52
	v_mov_b32_e32 v51, v50
	s_nop 1
	v_permlane16_swap_b32_e32 v50, v51
	v_max_f32_e32 v50, v50, v51
	v_mov_b32_e32 v51, v50
	s_nop 1
	v_permlane32_swap_b32_e32 v50, v51
	v_max_f32_e32 v50, v50, v51
	v_cmp_lt_f32_e32 vcc, s29, v50
	s_cbranch_vccz .LBB0_1349
	v_max_f32_e32 v51, 0, v50
	v_exp_f32_e64 v50, -v51
	v_sub_f32_e32 v52, v27, v51
	v_sub_f32_e32 v53, v28, v51
	v_add_f32_e32 v1, v1, v51
	v_pk_mul_f32 v[60:61], v[60:61], v[50:51] op_sel_hi:[1,0]
	v_pk_mul_f32 v[58:59], v[58:59], v[50:51] op_sel_hi:[1,0]
	v_pk_mul_f32 v[120:121], v[120:121], v[50:51] op_sel_hi:[1,0]
	v_pk_mul_f32 v[118:119], v[118:119], v[50:51] op_sel_hi:[1,0]
	v_pk_mul_f32 v[116:117], v[116:117], v[50:51] op_sel_hi:[1,0]
	v_pk_mul_f32 v[114:115], v[114:115], v[50:51] op_sel_hi:[1,0]
	v_pk_mul_f32 v[112:113], v[112:113], v[50:51] op_sel_hi:[1,0]
	v_pk_mul_f32 v[110:111], v[110:111], v[50:51] op_sel_hi:[1,0]
	v_pk_mul_f32 v[108:109], v[108:109], v[50:51] op_sel_hi:[1,0]
	v_pk_mul_f32 v[106:107], v[106:107], v[50:51] op_sel_hi:[1,0]
	v_sub_f32_e32 v50, v26, v51
	v_sub_f32_e32 v46, v46, v51
	v_sub_f32_e32 v47, v47, v51
	v_sub_f32_e32 v48, v48, v51
	v_sub_f32_e32 v49, v49, v51
	v_sub_f32_e32 v54, v29, v51
	v_cndmask_b32_e64 v28, v28, v53, s[10:11]
	v_cndmask_b32_e64 v27, v27, v52, s[10:11]
	v_cndmask_b32_e64 v26, v26, v50, s[10:11]
	v_sub_f32_e32 v42, v42, v51
	v_sub_f32_e32 v43, v43, v51
	v_sub_f32_e32 v44, v44, v51
	v_sub_f32_e32 v45, v45, v51
	v_sub_f32_e32 v50, v30, v51
	v_sub_f32_e32 v52, v31, v51
	v_sub_f32_e32 v53, v32, v51
	v_sub_f32_e32 v51, v33, v51
	v_cndmask_b32_e64 v29, v29, v54, s[10:11]
	v_cndmask_b32_e64 v33, v33, v51, s[10:11]
	v_cndmask_b32_e64 v32, v32, v53, s[10:11]
	v_cndmask_b32_e64 v31, v31, v52, s[10:11]
	v_cndmask_b32_e64 v30, v30, v50, s[10:11]
	s_branch .LBB0_1349
